# fourier_out spectrum loads: SGPR-base+offset form, issued three groups ahead into dedicated registers (was 8 dependent round trips per item); all cvt->MFMA distances padded to 2 wait states
# speedup vs baseline: 1.0062x; 1.0034x over previous
.LBB0_235:
	global_load_dwordx4 v[90:93], v[74:75], off
	global_load_dwordx4 v[94:97], v[72:73], off
	global_load_dwordx4 v[106:109], v[72:73], off offset:2048
	global_load_dwordx4 v[110:113], v[76:77], off
	v_add_u32_e32 v56, s9, v137
	v_mov_b32_e32 v131, v209
	s_ashr_i32 s11, s9, 31
	s_lshr_b32 s11, s11, 19
	s_add_i32 s11, s9, s11
	s_and_b32 s11, s11, 0xffffe000
	s_sub_i32 s11, s9, s11
	s_add_i32 s18, s11, -8
	s_add_i32 s0, s0, s3
	s_add_u32 s100, s84, s58
	s_addc_u32 s101, s85, 0
	v_add_u32_e32 v0, 0, v56
	v_max_i32_e32 v0, 8, v0
	v_add_u32_e32 v0, -8, v0
	v_min_u32_e32 v0, 0xffff, v0
	v_mul_u32_u24_e32 v208, 0xe00, v0
	v_lshl_add_u64 v[0:1], s[100:101], 0, v[208:209]
	v_lshl_add_u64 v[0:1], v[0:1], 0, v[130:131]
	global_load_dwordx4 v[0:3], v[0:1], off offset:1536
	v_add_u32_e32 v4, 2, v56
	v_max_i32_e32 v4, 8, v4
	v_add_u32_e32 v4, -8, v4
	v_min_u32_e32 v4, 0xffff, v4
	v_mul_u32_u24_e32 v208, 0xe00, v4
	v_lshl_add_u64 v[4:5], s[100:101], 0, v[208:209]
	v_lshl_add_u64 v[4:5], v[4:5], 0, v[130:131]
	global_load_dwordx4 v[4:7], v[4:5], off offset:1536
	v_add_u32_e32 v8, 4, v56
	v_max_i32_e32 v8, 8, v8
	v_add_u32_e32 v8, -8, v8
	v_min_u32_e32 v8, 0xffff, v8
	v_mul_u32_u24_e32 v208, 0xe00, v8
	v_lshl_add_u64 v[8:9], s[100:101], 0, v[208:209]
	v_lshl_add_u64 v[8:9], v[8:9], 0, v[130:131]
	global_load_dwordx4 v[8:11], v[8:9], off offset:1536
	v_add_u32_e32 v12, 6, v56
	v_max_i32_e32 v12, 8, v12
	v_add_u32_e32 v12, -8, v12
	v_min_u32_e32 v12, 0xffff, v12
	v_mul_u32_u24_e32 v208, 0xe00, v12
	v_lshl_add_u64 v[12:13], s[100:101], 0, v[208:209]
	v_lshl_add_u64 v[12:13], v[12:13], 0, v[130:131]
	global_load_dwordx4 v[12:15], v[12:13], off offset:1536
	v_add_u32_e32 v16, 8, v56
	v_max_i32_e32 v16, 8, v16
	v_add_u32_e32 v16, -8, v16
	v_min_u32_e32 v16, 0xffff, v16
	v_mul_u32_u24_e32 v208, 0xe00, v16
	v_lshl_add_u64 v[16:17], s[100:101], 0, v[208:209]
	v_lshl_add_u64 v[16:17], v[16:17], 0, v[130:131]
	global_load_dwordx4 v[16:19], v[16:17], off offset:1536
	v_add_u32_e32 v20, 10, v56
	v_max_i32_e32 v20, 8, v20
	v_add_u32_e32 v20, -8, v20
	v_min_u32_e32 v20, 0xffff, v20
	v_mul_u32_u24_e32 v208, 0xe00, v20
	v_lshl_add_u64 v[20:21], s[100:101], 0, v[208:209]
	v_lshl_add_u64 v[20:21], v[20:21], 0, v[130:131]
	global_load_dwordx4 v[20:23], v[20:21], off offset:1536
	v_add_u32_e32 v24, 12, v56
	v_max_i32_e32 v24, 8, v24
	v_add_u32_e32 v24, -8, v24
	v_min_u32_e32 v24, 0xffff, v24
	v_mul_u32_u24_e32 v208, 0xe00, v24
	v_lshl_add_u64 v[24:25], s[100:101], 0, v[208:209]
	v_lshl_add_u64 v[24:25], v[24:25], 0, v[130:131]
	global_load_dwordx4 v[24:27], v[24:25], off offset:1536
	v_add_u32_e32 v28, 14, v56
	v_max_i32_e32 v28, 8, v28
	v_add_u32_e32 v28, -8, v28
	v_min_u32_e32 v28, 0xffff, v28
	v_mul_u32_u24_e32 v208, 0xe00, v28
	v_lshl_add_u64 v[28:29], s[100:101], 0, v[208:209]
	v_lshl_add_u64 v[28:29], v[28:29], 0, v[130:131]
	global_load_dwordx4 v[28:31], v[28:29], off offset:1536
	v_add_u32_e32 v32, 16, v56
	v_max_i32_e32 v32, 8, v32
	v_add_u32_e32 v32, -8, v32
	v_min_u32_e32 v32, 0xffff, v32
	v_mul_u32_u24_e32 v208, 0xe00, v32
	v_lshl_add_u64 v[32:33], s[100:101], 0, v[208:209]
	v_lshl_add_u64 v[32:33], v[32:33], 0, v[130:131]
	global_load_dwordx4 v[32:35], v[32:33], off offset:1536
	v_add_u32_e32 v36, 18, v56
	v_max_i32_e32 v36, 8, v36
	v_add_u32_e32 v36, -8, v36
	v_min_u32_e32 v36, 0xffff, v36
	v_mul_u32_u24_e32 v208, 0xe00, v36
	v_lshl_add_u64 v[36:37], s[100:101], 0, v[208:209]
	v_lshl_add_u64 v[36:37], v[36:37], 0, v[130:131]
	global_load_dwordx4 v[36:39], v[36:37], off offset:1536
	v_add_u32_e32 v40, 20, v56
	v_max_i32_e32 v40, 8, v40
	v_add_u32_e32 v40, -8, v40
	v_min_u32_e32 v40, 0xffff, v40
	v_mul_u32_u24_e32 v208, 0xe00, v40
	v_lshl_add_u64 v[40:41], s[100:101], 0, v[208:209]
	v_lshl_add_u64 v[40:41], v[40:41], 0, v[130:131]
	global_load_dwordx4 v[40:43], v[40:41], off offset:1536
	v_add_u32_e32 v44, 22, v56
	v_max_i32_e32 v44, 8, v44
	v_add_u32_e32 v44, -8, v44
	v_min_u32_e32 v44, 0xffff, v44
	v_mul_u32_u24_e32 v208, 0xe00, v44
	v_lshl_add_u64 v[44:45], s[100:101], 0, v[208:209]
	v_lshl_add_u64 v[44:45], v[44:45], 0, v[130:131]
	global_load_dwordx4 v[44:47], v[44:45], off offset:1536
	v_add_u32_e32 v48, 24, v56
	v_max_i32_e32 v48, 8, v48
	v_add_u32_e32 v48, -8, v48
	v_min_u32_e32 v48, 0xffff, v48
	v_mul_u32_u24_e32 v208, 0xe00, v48
	v_lshl_add_u64 v[48:49], s[100:101], 0, v[208:209]
	v_lshl_add_u64 v[48:49], v[48:49], 0, v[130:131]
	global_load_dwordx4 v[48:51], v[48:49], off offset:1536
	v_add_u32_e32 v52, 26, v56
	v_max_i32_e32 v52, 8, v52
	v_add_u32_e32 v52, -8, v52
	v_min_u32_e32 v52, 0xffff, v52
	v_mul_u32_u24_e32 v208, 0xe00, v52
	v_lshl_add_u64 v[52:53], s[100:101], 0, v[208:209]
	v_lshl_add_u64 v[52:53], v[52:53], 0, v[130:131]
	global_load_dwordx4 v[52:55], v[52:53], off offset:1536
	v_add_u32_e32 v58, 28, v56
	v_max_i32_e32 v58, 8, v58
	v_add_u32_e32 v58, -8, v58
	v_min_u32_e32 v58, 0xffff, v58
	v_mul_u32_u24_e32 v208, 0xe00, v58
	v_lshl_add_u64 v[58:59], s[100:101], 0, v[208:209]
	v_lshl_add_u64 v[58:59], v[58:59], 0, v[130:131]
	global_load_dwordx4 v[58:61], v[58:59], off offset:1536
	v_add_u32_e32 v62, 30, v56
	v_max_i32_e32 v62, 8, v62
	v_add_u32_e32 v62, -8, v62
	v_min_u32_e32 v62, 0xffff, v62
	v_mul_u32_u24_e32 v208, 0xe00, v62
	v_lshl_add_u64 v[62:63], s[100:101], 0, v[208:209]
	v_lshl_add_u64 v[62:63], v[62:63], 0, v[130:131]
	global_load_dwordx4 v[62:65], v[62:63], off offset:1536
	s_cmpk_lt_u32 s18, 0x2000
	s_cselect_b64 vcc, -1, 0
	s_waitcnt vmcnt(15)
	v_cndmask_b32_e32 v3, 0, v3, vcc
	v_cndmask_b32_e32 v2, 0, v2, vcc
	v_cndmask_b32_e32 v1, 0, v1, vcc
	v_cndmask_b32_e32 v0, 0, v0, vcc
	s_waitcnt vmcnt(14)
	v_cndmask_b32_e32 v7, 0, v7, vcc
	v_cndmask_b32_e32 v6, 0, v6, vcc
	v_cndmask_b32_e32 v5, 0, v5, vcc
	v_cndmask_b32_e32 v4, 0, v4, vcc
	s_waitcnt vmcnt(13)
	v_cndmask_b32_e32 v11, 0, v11, vcc
	v_cndmask_b32_e32 v10, 0, v10, vcc
	v_cndmask_b32_e32 v9, 0, v9, vcc
	v_cndmask_b32_e32 v8, 0, v8, vcc
	s_waitcnt vmcnt(12)
	v_cndmask_b32_e32 v15, 0, v15, vcc
	v_cndmask_b32_e32 v14, 0, v14, vcc
	v_cndmask_b32_e32 v13, 0, v13, vcc
	v_cndmask_b32_e32 v12, 0, v12, vcc
	s_cmp_gt_i32 s11, -1
	s_cselect_b64 vcc, -1, 0
	s_waitcnt vmcnt(11)
	v_cndmask_b32_e32 v19, 0, v19, vcc
	v_cndmask_b32_e32 v18, 0, v18, vcc
	v_cndmask_b32_e32 v17, 0, v17, vcc
	v_cndmask_b32_e32 v16, 0, v16, vcc
	v_add_u32_e32 v206, s18, v138
	v_cmp_gt_u32_e32 vcc, s15, v206
	s_waitcnt vmcnt(10)
	s_nop 0
	v_cndmask_b32_e32 v23, 0, v23, vcc
	v_cndmask_b32_e32 v22, 0, v22, vcc
	v_cndmask_b32_e32 v21, 0, v21, vcc
	v_cndmask_b32_e32 v20, 0, v20, vcc
	v_add_u32_e32 v206, s18, v139
	v_cmp_gt_u32_e32 vcc, s15, v206
	s_waitcnt vmcnt(9)
	s_nop 0
	v_cndmask_b32_e32 v27, 0, v27, vcc
	v_cndmask_b32_e32 v26, 0, v26, vcc
	v_cndmask_b32_e32 v25, 0, v25, vcc
	v_cndmask_b32_e32 v24, 0, v24, vcc
	v_add_u32_e32 v206, s18, v140
	v_cmp_gt_u32_e32 vcc, s15, v206
	s_waitcnt vmcnt(8)
	s_nop 0
	v_cndmask_b32_e32 v31, 0, v31, vcc
	v_cndmask_b32_e32 v30, 0, v30, vcc
	v_cndmask_b32_e32 v29, 0, v29, vcc
	v_cndmask_b32_e32 v28, 0, v28, vcc
	v_add_u32_e32 v206, s18, v141
	v_cmp_gt_u32_e32 vcc, s15, v206
	s_waitcnt vmcnt(7)
	s_nop 0
	v_cndmask_b32_e32 v35, 0, v35, vcc
	v_cndmask_b32_e32 v34, 0, v34, vcc
	v_cndmask_b32_e32 v33, 0, v33, vcc
	v_cndmask_b32_e32 v32, 0, v32, vcc
	v_add_u32_e32 v206, s18, v142
	v_cmp_gt_u32_e32 vcc, s15, v206
	s_waitcnt vmcnt(6)
	s_nop 0
	v_cndmask_b32_e32 v39, 0, v39, vcc
	v_cndmask_b32_e32 v38, 0, v38, vcc
	v_cndmask_b32_e32 v37, 0, v37, vcc
	v_cndmask_b32_e32 v36, 0, v36, vcc
	v_add_u32_e32 v206, s18, v143
	v_cmp_gt_u32_e32 vcc, s15, v206
	s_waitcnt vmcnt(5)
	s_nop 0
	v_cndmask_b32_e32 v43, 0, v43, vcc
	v_cndmask_b32_e32 v42, 0, v42, vcc
	v_cndmask_b32_e32 v41, 0, v41, vcc
	v_cndmask_b32_e32 v40, 0, v40, vcc
	v_add_u32_e32 v206, s18, v144
	v_cmp_gt_u32_e32 vcc, s15, v206
	s_waitcnt vmcnt(4)
	s_nop 0
	v_cndmask_b32_e32 v47, 0, v47, vcc
	v_cndmask_b32_e32 v46, 0, v46, vcc
	v_cndmask_b32_e32 v45, 0, v45, vcc
	v_cndmask_b32_e32 v44, 0, v44, vcc
	v_add_u32_e32 v206, s18, v145
	v_cmp_gt_u32_e32 vcc, s15, v206
	s_waitcnt vmcnt(3)
	s_nop 0
	v_cndmask_b32_e32 v51, 0, v51, vcc
	v_cndmask_b32_e32 v50, 0, v50, vcc
	v_cndmask_b32_e32 v49, 0, v49, vcc
	v_cndmask_b32_e32 v48, 0, v48, vcc
	v_add_u32_e32 v206, s18, v146
	v_cmp_gt_u32_e32 vcc, s15, v206
	s_waitcnt vmcnt(2)
	s_nop 0
	v_cndmask_b32_e32 v55, 0, v55, vcc
	v_cndmask_b32_e32 v54, 0, v54, vcc
	v_cndmask_b32_e32 v53, 0, v53, vcc
	v_cndmask_b32_e32 v52, 0, v52, vcc
	v_add_u32_e32 v206, s18, v147
	v_cmp_gt_u32_e32 vcc, s15, v206
	s_waitcnt vmcnt(1)
	s_nop 0
	v_cndmask_b32_e32 v61, 0, v61, vcc
	v_cndmask_b32_e32 v60, 0, v60, vcc
	v_cndmask_b32_e32 v59, 0, v59, vcc
	v_cndmask_b32_e32 v58, 0, v58, vcc
	v_add_u32_e32 v206, s18, v148
	v_cmp_gt_u32_e32 vcc, s15, v206
	s_waitcnt vmcnt(0)
	s_nop 0
	v_cndmask_b32_e32 v65, 0, v65, vcc
	v_cndmask_b32_e32 v64, 0, v64, vcc
	v_cndmask_b32_e32 v63, 0, v63, vcc
	v_cndmask_b32_e32 v62, 0, v62, vcc
	v_or_b32_e32 v56, s11, v136
	ds_write_b128 v150, v[0:3]
	ds_write_b128 v150, v[4:7] offset:1056
	ds_write_b128 v150, v[8:11] offset:2112
	ds_write_b128 v150, v[12:15] offset:3168
	ds_write_b128 v150, v[16:19] offset:4224
	ds_write_b128 v150, v[20:23] offset:5280
	ds_write_b128 v150, v[24:27] offset:6336
	ds_write_b128 v150, v[28:31] offset:7392
	ds_write_b128 v150, v[32:35] offset:8448
	ds_write_b128 v150, v[36:39] offset:9504
	ds_write_b128 v150, v[40:43] offset:10560
	ds_write_b128 v150, v[44:47] offset:11616
	ds_write_b128 v150, v[48:51] offset:12672
	ds_write_b128 v150, v[52:55] offset:13728
	ds_write_b128 v150, v[58:61] offset:14784
	ds_write_b128 v150, v[62:65] offset:15840
	v_add_u32_e32 v0, s9, v136
	v_ashrrev_i32_e32 v1, 31, v0
	v_lshlrev_b64 v[134:135], 11, v[0:1]
	v_max_i32_e32 v0, 1, v56
	v_min_i32_e32 v1, 0x1fff, v56
	v_sub_u32_e32 v0, v1, v0
	v_add_u32_e32 v0, 2, v0
	v_cvt_f32_i32_e32 v0, v0
	s_waitcnt lgkmcnt(0)
	s_add_i32 s9, s9, s17
	s_cmpk_lt_i32 s0, 0x1000
	v_div_scale_f32 v1, s[18:19], v0, v0, 1.0
	v_rcp_f32_e32 v2, v1
	s_nop 0
	v_fma_f32 v3, -v1, v2, 1.0
	v_fmac_f32_e32 v2, v3, v2
	v_div_scale_f32 v3, vcc, 1.0, v0, 1.0
	v_mul_f32_e32 v4, v3, v2
	v_fma_f32 v5, -v1, v4, v3
	v_fmac_f32_e32 v4, v5, v2
	v_fma_f32 v1, -v1, v4, v3
	v_div_fmas_f32 v1, v1, v2, v4
	v_div_fixup_f32 v20, v1, v0, 1.0
	ds_read_b128 v[0:3], v149 offset:3696
	s_waitcnt lgkmcnt(0)
	v_lshlrev_b32_e32 v4, 16, v0
	v_and_b32_e32 v0, 0xffff0000, v0
	v_lshlrev_b32_e32 v5, 16, v1
	v_and_b32_e32 v1, 0xffff0000, v1
	v_lshlrev_b32_e32 v6, 16, v2
	v_and_b32_e32 v2, 0xffff0000, v2
	v_lshlrev_b32_e32 v7, 16, v3
	v_and_b32_e32 v3, 0xffff0000, v3
	v_add_f32_e32 v8, 0, v0
	v_add_f32_e32 v9, 0, v1
	v_add_f32_e32 v10, 0, v2
	v_add_f32_e32 v11, 0, v3
	ds_read_b128 v[0:3], v149 offset:4224
	v_add_f32_e32 v4, 0, v4
	v_add_f32_e32 v5, 0, v5
	v_add_f32_e32 v6, 0, v6
	v_add_f32_e32 v7, 0, v7
	s_waitcnt lgkmcnt(0)
	v_lshlrev_b32_e32 v12, 16, v0
	v_and_b32_e32 v0, 0xffff0000, v0
	v_lshlrev_b32_e32 v13, 16, v1
	v_and_b32_e32 v1, 0xffff0000, v1
	v_lshlrev_b32_e32 v14, 16, v2
	v_and_b32_e32 v2, 0xffff0000, v2
	v_lshlrev_b32_e32 v15, 16, v3
	v_and_b32_e32 v3, 0xffff0000, v3
	v_add_f32_e32 v8, v8, v0
	v_add_f32_e32 v9, v9, v1
	v_add_f32_e32 v10, v10, v2
	v_add_f32_e32 v11, v11, v3
	v_add_f32_e32 v4, v4, v12
	v_add_f32_e32 v5, v5, v13
	v_add_f32_e32 v6, v6, v14
	v_add_f32_e32 v7, v7, v15
	v_fma_f32 v0, v20, v8, -v0
	v_fma_f32 v1, v20, v9, -v1
	v_fma_f32 v2, v20, v10, -v2
	v_fma_f32 v3, v20, v11, -v3
	v_fma_f32 v4, v20, v4, -v12
	v_fma_f32 v5, v20, v5, -v13
	v_fma_f32 v6, v20, v6, -v14
	v_fma_f32 v7, v20, v7, -v15
	v_cvt_pk_bf16_f32 v0, v4, v0
	v_cvt_pk_bf16_f32 v1, v5, v1
	v_cvt_pk_bf16_f32 v2, v6, v2
	v_cvt_pk_bf16_f32 v3, v7, v3
	s_waitcnt vmcnt(2)
	s_nop 0
	v_mfma_f32_16x16x32_bf16 v[16:19], v[90:93], v[0:3], 0
	s_waitcnt vmcnt(2)
	v_mfma_f32_16x16x32_bf16 v[4:7], v[94:97], v[0:3], 0
	s_waitcnt vmcnt(1)
	v_mfma_f32_16x16x32_bf16 v[8:11], v[106:109], v[0:3], 0
	s_waitcnt vmcnt(0)
	v_mfma_f32_16x16x32_bf16 v[0:3], v[110:113], v[0:3], 0
	global_load_dwordx4 v[90:93], v[86:87], off
	global_load_dwordx4 v[94:97], v[82:83], off
	global_load_dwordx4 v[106:109], v[84:85], off
	global_load_dwordx4 v[110:113], v[88:89], off
	ds_read_b128 v[12:15], v149 offset:3760
	s_waitcnt lgkmcnt(0)
	v_lshlrev_b32_e32 v21, 16, v12
	v_and_b32_e32 v12, 0xffff0000, v12
	v_lshlrev_b32_e32 v22, 16, v13
	v_and_b32_e32 v13, 0xffff0000, v13
	v_lshlrev_b32_e32 v23, 16, v14
	v_and_b32_e32 v14, 0xffff0000, v14
	v_lshlrev_b32_e32 v24, 16, v15
	v_and_b32_e32 v15, 0xffff0000, v15
	v_add_f32_e32 v25, 0, v12
	v_add_f32_e32 v26, 0, v13
	v_add_f32_e32 v27, 0, v14
	v_add_f32_e32 v28, 0, v15
	ds_read_b128 v[12:15], v149 offset:4288
	v_add_f32_e32 v21, 0, v21
	v_add_f32_e32 v22, 0, v22
	v_add_f32_e32 v23, 0, v23
	v_add_f32_e32 v24, 0, v24
	s_waitcnt lgkmcnt(0)
	v_lshlrev_b32_e32 v29, 16, v12
	v_and_b32_e32 v12, 0xffff0000, v12
	v_lshlrev_b32_e32 v30, 16, v13
	v_and_b32_e32 v13, 0xffff0000, v13
	v_lshlrev_b32_e32 v31, 16, v14
	v_and_b32_e32 v14, 0xffff0000, v14
	v_lshlrev_b32_e32 v32, 16, v15
	v_and_b32_e32 v15, 0xffff0000, v15
	v_add_f32_e32 v21, v21, v29
	v_add_f32_e32 v25, v25, v12
	v_add_f32_e32 v22, v22, v30
	v_add_f32_e32 v26, v26, v13
	v_add_f32_e32 v23, v23, v31
	v_add_f32_e32 v27, v27, v14
	v_add_f32_e32 v28, v28, v15
	v_add_f32_e32 v24, v24, v32
	v_fma_f32 v21, v20, v21, -v29
	v_fma_f32 v12, v20, v25, -v12
	v_fma_f32 v22, v20, v22, -v30
	v_fma_f32 v13, v20, v26, -v13
	v_fma_f32 v23, v20, v23, -v31
	v_fma_f32 v14, v20, v27, -v14
	v_fma_f32 v15, v20, v28, -v15
	v_fma_f32 v24, v20, v24, -v32
	v_cvt_pk_bf16_f32 v20, v21, v12
	v_cvt_pk_bf16_f32 v21, v22, v13
	v_cvt_pk_bf16_f32 v22, v23, v14
	v_cvt_pk_bf16_f32 v23, v24, v15
	s_waitcnt vmcnt(0)
	s_nop 0
	v_mfma_f32_16x16x32_bf16 v[12:15], v[166:169], v[20:23], v[4:7]
	s_nop 2
	s_waitcnt vmcnt(0)
	v_mfma_f32_16x16x32_bf16 v[8:11], v[170:173], v[20:23], v[8:11]
	s_waitcnt vmcnt(0)
	v_mfma_f32_16x16x32_bf16 v[4:7], v[174:177], v[20:23], v[16:19]
	s_nop 2
	s_waitcnt vmcnt(0)
	v_mfma_f32_16x16x32_bf16 v[0:3], v[178:181], v[20:23], v[0:3]
	v_max_i32_e32 v16, 2, v56
	v_min_i32_e32 v17, 0x1ffe, v56
	v_sub_u32_e32 v16, v17, v16
	v_add_u32_e32 v16, 4, v16
	v_cvt_f32_i32_e32 v16, v16
	v_div_scale_f32 v17, s[18:19], v16, v16, 1.0
	v_rcp_f32_e32 v18, v17
	s_nop 0
	v_fma_f32 v19, -v17, v18, 1.0
	v_fmac_f32_e32 v18, v19, v18
	v_div_scale_f32 v19, vcc, 1.0, v16, 1.0
	v_mul_f32_e32 v20, v19, v18
	v_fma_f32 v21, -v17, v20, v19
	v_fmac_f32_e32 v20, v21, v18
	v_fma_f32 v17, -v17, v20, v19
	v_div_fmas_f32 v17, v17, v18, v20
	v_div_fixup_f32 v36, v17, v16, 1.0
	ds_read_b128 v[16:19], v149 offset:3296
	s_waitcnt lgkmcnt(0)
	v_lshlrev_b32_e32 v20, 16, v16
	v_and_b32_e32 v16, 0xffff0000, v16
	v_lshlrev_b32_e32 v21, 16, v17
	v_and_b32_e32 v17, 0xffff0000, v17
	v_lshlrev_b32_e32 v22, 16, v18
	v_and_b32_e32 v18, 0xffff0000, v18
	v_lshlrev_b32_e32 v23, 16, v19
	v_and_b32_e32 v19, 0xffff0000, v19
	v_add_f32_e32 v24, 0, v16
	v_add_f32_e32 v25, 0, v17
	v_add_f32_e32 v26, 0, v18
	v_add_f32_e32 v27, 0, v19
	ds_read_b128 v[16:19], v149 offset:3824
	v_add_f32_e32 v20, 0, v20
	v_add_f32_e32 v21, 0, v21
	v_add_f32_e32 v22, 0, v22
	v_add_f32_e32 v23, 0, v23
	s_waitcnt lgkmcnt(0)
	v_lshlrev_b32_e32 v28, 16, v16
	v_and_b32_e32 v16, 0xffff0000, v16
	v_lshlrev_b32_e32 v29, 16, v17
	v_and_b32_e32 v17, 0xffff0000, v17
	v_lshlrev_b32_e32 v30, 16, v18
	v_and_b32_e32 v18, 0xffff0000, v18
	v_lshlrev_b32_e32 v31, 16, v19
	v_and_b32_e32 v19, 0xffff0000, v19
	v_add_f32_e32 v24, v24, v16
	v_add_f32_e32 v25, v25, v17
	v_add_f32_e32 v26, v26, v18
	v_add_f32_e32 v27, v27, v19
	ds_read_b128 v[16:19], v149 offset:4352
	v_add_f32_e32 v20, v20, v28
	v_add_f32_e32 v21, v21, v29
	v_add_f32_e32 v22, v22, v30
	v_add_f32_e32 v23, v23, v31
	s_waitcnt lgkmcnt(0)
	v_lshlrev_b32_e32 v28, 16, v16
	v_and_b32_e32 v29, 0xffff0000, v16
	v_lshlrev_b32_e32 v30, 16, v17
	v_and_b32_e32 v31, 0xffff0000, v17
	v_lshlrev_b32_e32 v32, 16, v18
	v_and_b32_e32 v33, 0xffff0000, v18
	v_lshlrev_b32_e32 v34, 16, v19
	v_and_b32_e32 v35, 0xffff0000, v19
	ds_read_b128 v[16:19], v149 offset:4880
	v_add_f32_e32 v24, v24, v29
	v_add_f32_e32 v25, v25, v31
	v_add_f32_e32 v26, v26, v33
	v_add_f32_e32 v27, v27, v35
	s_waitcnt lgkmcnt(0)
	v_lshlrev_b32_e32 v37, 16, v16
	v_and_b32_e32 v16, 0xffff0000, v16
	v_lshlrev_b32_e32 v38, 16, v17
	v_and_b32_e32 v17, 0xffff0000, v17
	v_lshlrev_b32_e32 v39, 16, v18
	v_and_b32_e32 v18, 0xffff0000, v18
	v_lshlrev_b32_e32 v40, 16, v19
	v_and_b32_e32 v19, 0xffff0000, v19
	v_add_f32_e32 v20, v20, v28
	v_add_f32_e32 v21, v21, v30
	v_add_f32_e32 v22, v22, v32
	v_add_f32_e32 v23, v23, v34
	v_add_f32_e32 v16, v24, v16
	v_add_f32_e32 v17, v25, v17
	v_add_f32_e32 v18, v26, v18
	v_add_f32_e32 v19, v27, v19
	v_add_f32_e32 v20, v20, v37
	v_add_f32_e32 v21, v21, v38
	v_add_f32_e32 v22, v22, v39
	v_add_f32_e32 v23, v23, v40
	v_fma_f32 v16, v36, v16, -v29
	v_fma_f32 v17, v36, v17, -v31
	v_fma_f32 v18, v36, v18, -v33
	v_fma_f32 v19, v36, v19, -v35
	v_fma_f32 v20, v36, v20, -v28
	v_fma_f32 v21, v36, v21, -v30
	v_fma_f32 v22, v36, v22, -v32
	v_fma_f32 v23, v36, v23, -v34
	v_cvt_pk_bf16_f32 v16, v20, v16
	v_cvt_pk_bf16_f32 v17, v21, v17
	v_cvt_pk_bf16_f32 v18, v22, v18
	v_cvt_pk_bf16_f32 v19, v23, v19
	s_waitcnt vmcnt(2)
	s_nop 0
	v_mfma_f32_16x16x32_bf16 v[32:35], v[90:93], v[16:19], 0
	s_waitcnt vmcnt(2)
	v_mfma_f32_16x16x32_bf16 v[20:23], v[94:97], v[16:19], 0
	s_waitcnt vmcnt(1)
	v_mfma_f32_16x16x32_bf16 v[24:27], v[106:109], v[16:19], 0
	s_waitcnt vmcnt(0)
	v_mfma_f32_16x16x32_bf16 v[16:19], v[110:113], v[16:19], 0
	global_load_dwordx4 v[90:93], v[98:99], off
	global_load_dwordx4 v[94:97], v[100:101], off
	global_load_dwordx4 v[106:109], v[102:103], off
	global_load_dwordx4 v[110:113], v[104:105], off
	ds_read_b128 v[28:31], v149 offset:3360
	s_waitcnt lgkmcnt(0)
	v_lshlrev_b32_e32 v37, 16, v28
	v_and_b32_e32 v28, 0xffff0000, v28
	v_lshlrev_b32_e32 v38, 16, v29
	v_and_b32_e32 v29, 0xffff0000, v29
	v_lshlrev_b32_e32 v39, 16, v30
	v_and_b32_e32 v30, 0xffff0000, v30
	v_lshlrev_b32_e32 v40, 16, v31
	v_and_b32_e32 v31, 0xffff0000, v31
	v_add_f32_e32 v41, 0, v28
	v_add_f32_e32 v42, 0, v29
	v_add_f32_e32 v43, 0, v30
	v_add_f32_e32 v44, 0, v31
	ds_read_b128 v[28:31], v149 offset:3888
	v_add_f32_e32 v37, 0, v37
	v_add_f32_e32 v38, 0, v38
	v_add_f32_e32 v39, 0, v39
	v_add_f32_e32 v40, 0, v40
	s_waitcnt lgkmcnt(0)
	v_lshlrev_b32_e32 v45, 16, v28
	v_and_b32_e32 v28, 0xffff0000, v28
	v_lshlrev_b32_e32 v46, 16, v29
	v_and_b32_e32 v29, 0xffff0000, v29
	v_lshlrev_b32_e32 v47, 16, v30
	v_and_b32_e32 v30, 0xffff0000, v30
	v_lshlrev_b32_e32 v48, 16, v31
	v_and_b32_e32 v31, 0xffff0000, v31
	v_add_f32_e32 v41, v41, v28
	v_add_f32_e32 v42, v42, v29
	v_add_f32_e32 v43, v43, v30
	v_add_f32_e32 v44, v44, v31
	ds_read_b128 v[28:31], v149 offset:4416
	v_add_f32_e32 v37, v37, v45
	v_add_f32_e32 v38, v38, v46
	v_add_f32_e32 v39, v39, v47
	v_add_f32_e32 v40, v40, v48
	s_waitcnt lgkmcnt(0)
	v_lshlrev_b32_e32 v45, 16, v28
	v_and_b32_e32 v46, 0xffff0000, v28
	v_lshlrev_b32_e32 v47, 16, v29
	v_and_b32_e32 v48, 0xffff0000, v29
	v_lshlrev_b32_e32 v49, 16, v30
	v_and_b32_e32 v50, 0xffff0000, v30
	v_lshlrev_b32_e32 v51, 16, v31
	v_and_b32_e32 v52, 0xffff0000, v31
	ds_read_b128 v[28:31], v149 offset:4944
	v_add_f32_e32 v37, v37, v45
	v_add_f32_e32 v41, v41, v46
	v_add_f32_e32 v38, v38, v47
	v_add_f32_e32 v42, v42, v48
	v_add_f32_e32 v39, v39, v49
	v_add_f32_e32 v43, v43, v50
	v_add_f32_e32 v44, v44, v52
	s_waitcnt lgkmcnt(0)
	v_lshlrev_b32_e32 v53, 16, v28
	v_and_b32_e32 v28, 0xffff0000, v28
	v_lshlrev_b32_e32 v54, 16, v29
	v_and_b32_e32 v29, 0xffff0000, v29
	v_lshlrev_b32_e32 v55, 16, v30
	v_and_b32_e32 v30, 0xffff0000, v30
	v_lshlrev_b32_e32 v57, 16, v31
	v_and_b32_e32 v31, 0xffff0000, v31
	v_add_f32_e32 v40, v40, v51
	v_add_f32_e32 v37, v37, v53
	v_add_f32_e32 v28, v41, v28
	v_add_f32_e32 v38, v38, v54
	v_add_f32_e32 v29, v42, v29
	v_add_f32_e32 v39, v39, v55
	v_add_f32_e32 v30, v43, v30
	v_add_f32_e32 v31, v44, v31
	v_add_f32_e32 v40, v40, v57
	v_fma_f32 v37, v36, v37, -v45
	v_fma_f32 v28, v36, v28, -v46
	v_fma_f32 v38, v36, v38, -v47
	v_fma_f32 v29, v36, v29, -v48
	v_fma_f32 v39, v36, v39, -v49
	v_fma_f32 v30, v36, v30, -v50
	v_fma_f32 v31, v36, v31, -v52
	v_fma_f32 v40, v36, v40, -v51
	v_cvt_pk_bf16_f32 v36, v37, v28
	v_cvt_pk_bf16_f32 v37, v38, v29
	v_cvt_pk_bf16_f32 v38, v39, v30
	v_cvt_pk_bf16_f32 v39, v40, v31
	s_waitcnt vmcnt(0)
	s_nop 0
	v_mfma_f32_16x16x32_bf16 v[28:31], v[182:185], v[36:39], v[20:23]
	s_nop 2
	s_waitcnt vmcnt(0)
	v_mfma_f32_16x16x32_bf16 v[24:27], v[186:189], v[36:39], v[24:27]
	s_waitcnt vmcnt(0)
	v_mfma_f32_16x16x32_bf16 v[20:23], v[190:193], v[36:39], v[32:35]
	s_nop 2
	s_waitcnt vmcnt(0)
	v_mfma_f32_16x16x32_bf16 v[16:19], v[194:197], v[36:39], v[16:19]
	v_max_i32_e32 v32, 4, v56
	v_min_i32_e32 v33, 0x1ffc, v56
	v_sub_u32_e32 v32, v33, v32
	v_add_u32_e32 v32, 8, v32
	v_cvt_f32_i32_e32 v32, v32
	v_div_scale_f32 v33, s[18:19], v32, v32, 1.0
	v_rcp_f32_e32 v34, v33
	s_nop 0
	v_fma_f32 v35, -v33, v34, 1.0
	v_fmac_f32_e32 v34, v35, v34
	v_div_scale_f32 v35, vcc, 1.0, v32, 1.0
	v_mul_f32_e32 v36, v35, v34
	v_fma_f32 v37, -v33, v36, v35
	v_fmac_f32_e32 v36, v37, v34
	v_fma_f32 v33, -v33, v36, v35
	v_div_fmas_f32 v33, v33, v34, v36
	v_div_fixup_f32 v40, v33, v32, 1.0
	ds_read_b128 v[32:35], v149 offset:2368
	s_waitcnt lgkmcnt(0)
	v_lshlrev_b32_e32 v36, 16, v32
	v_and_b32_e32 v32, 0xffff0000, v32
	v_lshlrev_b32_e32 v37, 16, v33
	v_and_b32_e32 v33, 0xffff0000, v33
	v_lshlrev_b32_e32 v38, 16, v34
	v_and_b32_e32 v34, 0xffff0000, v34
	v_lshlrev_b32_e32 v39, 16, v35
	v_and_b32_e32 v35, 0xffff0000, v35
	v_add_f32_e32 v41, 0, v32
	v_add_f32_e32 v42, 0, v33
	v_add_f32_e32 v43, 0, v34
	v_add_f32_e32 v44, 0, v35
	ds_read_b128 v[32:35], v149 offset:2896
	v_add_f32_e32 v36, 0, v36
	v_add_f32_e32 v37, 0, v37
	v_add_f32_e32 v38, 0, v38
	v_add_f32_e32 v39, 0, v39
	s_waitcnt lgkmcnt(0)
	v_lshlrev_b32_e32 v45, 16, v32
	v_and_b32_e32 v32, 0xffff0000, v32
	v_lshlrev_b32_e32 v46, 16, v33
	v_and_b32_e32 v33, 0xffff0000, v33
	v_lshlrev_b32_e32 v47, 16, v34
	v_and_b32_e32 v34, 0xffff0000, v34
	v_lshlrev_b32_e32 v48, 16, v35
	v_and_b32_e32 v35, 0xffff0000, v35
	v_add_f32_e32 v41, v41, v32
	v_add_f32_e32 v42, v42, v33
	v_add_f32_e32 v43, v43, v34
	v_add_f32_e32 v44, v44, v35
	ds_read_b128 v[32:35], v149 offset:3424
	v_add_f32_e32 v36, v36, v45
	v_add_f32_e32 v37, v37, v46
	v_add_f32_e32 v38, v38, v47
	v_add_f32_e32 v39, v39, v48
	s_waitcnt lgkmcnt(0)
	v_lshlrev_b32_e32 v45, 16, v32
	v_and_b32_e32 v32, 0xffff0000, v32
	v_lshlrev_b32_e32 v46, 16, v33
	v_and_b32_e32 v33, 0xffff0000, v33
	v_lshlrev_b32_e32 v47, 16, v34
	v_and_b32_e32 v34, 0xffff0000, v34
	v_lshlrev_b32_e32 v48, 16, v35
	v_and_b32_e32 v35, 0xffff0000, v35
	v_add_f32_e32 v41, v41, v32
	v_add_f32_e32 v42, v42, v33
	v_add_f32_e32 v43, v43, v34
	v_add_f32_e32 v44, v44, v35
	ds_read_b128 v[32:35], v149 offset:3952
	v_add_f32_e32 v36, v36, v45
	v_add_f32_e32 v37, v37, v46
	v_add_f32_e32 v38, v38, v47
	v_add_f32_e32 v39, v39, v48
	s_waitcnt lgkmcnt(0)
	v_lshlrev_b32_e32 v45, 16, v32
	v_lshlrev_b32_e32 v46, 16, v33
	v_lshlrev_b32_e32 v47, 16, v34
	v_lshlrev_b32_e32 v48, 16, v35
	v_add_f32_e32 v45, v36, v45
	v_add_f32_e32 v46, v37, v46
	v_add_f32_e32 v47, v38, v47
	v_add_f32_e32 v48, v39, v48
	ds_read_b128 v[36:39], v149 offset:4480
	v_and_b32_e32 v32, 0xffff0000, v32
	v_and_b32_e32 v33, 0xffff0000, v33
	v_and_b32_e32 v34, 0xffff0000, v34
	v_and_b32_e32 v35, 0xffff0000, v35
	v_add_f32_e32 v41, v41, v32
	v_add_f32_e32 v42, v42, v33
	v_add_f32_e32 v43, v43, v34
	v_add_f32_e32 v44, v44, v35
	s_waitcnt lgkmcnt(0)
	v_lshlrev_b32_e32 v32, 16, v36
	v_and_b32_e32 v33, 0xffff0000, v36
	v_lshlrev_b32_e32 v34, 16, v37
	v_and_b32_e32 v35, 0xffff0000, v37
	v_lshlrev_b32_e32 v36, 16, v38
	v_and_b32_e32 v37, 0xffff0000, v38
	v_lshlrev_b32_e32 v38, 16, v39
	v_and_b32_e32 v39, 0xffff0000, v39
	v_add_f32_e32 v49, v45, v32
	v_add_f32_e32 v50, v42, v35
	v_add_f32_e32 v51, v43, v37
	v_add_f32_e32 v52, v44, v39
	ds_read_b128 v[42:45], v149 offset:5008
	v_add_f32_e32 v41, v41, v33
	v_add_f32_e32 v46, v46, v34
	v_add_f32_e32 v47, v47, v36
	v_add_f32_e32 v48, v48, v38
	s_waitcnt lgkmcnt(0)
	v_lshlrev_b32_e32 v53, 16, v42
	v_and_b32_e32 v42, 0xffff0000, v42
	v_lshlrev_b32_e32 v54, 16, v43
	v_and_b32_e32 v43, 0xffff0000, v43
	v_lshlrev_b32_e32 v55, 16, v44
	v_and_b32_e32 v44, 0xffff0000, v44
	v_lshlrev_b32_e32 v57, 16, v45
	v_and_b32_e32 v45, 0xffff0000, v45
	v_add_f32_e32 v49, v49, v53
	v_add_f32_e32 v53, v41, v42
	v_add_f32_e32 v50, v50, v43
	v_add_f32_e32 v51, v51, v44
	v_add_f32_e32 v52, v52, v45
	ds_read_b128 v[42:45], v149 offset:5536
	v_add_f32_e32 v46, v46, v54
	v_add_f32_e32 v47, v47, v55
	v_add_f32_e32 v48, v48, v57
	s_waitcnt lgkmcnt(0)
	v_lshlrev_b32_e32 v41, 16, v42
	v_and_b32_e32 v42, 0xffff0000, v42
	v_lshlrev_b32_e32 v54, 16, v43
	v_and_b32_e32 v55, 0xffff0000, v43
	v_lshlrev_b32_e32 v57, 16, v44
	v_and_b32_e32 v58, 0xffff0000, v44
	v_lshlrev_b32_e32 v59, 16, v45
	v_and_b32_e32 v60, 0xffff0000, v45
	v_add_f32_e32 v42, v53, v42
	v_add_f32_e32 v43, v46, v54
	v_add_f32_e32 v44, v50, v55
	v_add_f32_e32 v45, v47, v57
	v_add_f32_e32 v46, v51, v58
	v_add_f32_e32 v47, v48, v59
	v_add_f32_e32 v48, v52, v60
	ds_read_b128 v[50:53], v149 offset:6064
	v_add_f32_e32 v41, v49, v41
	s_waitcnt lgkmcnt(0)
	v_lshlrev_b32_e32 v49, 16, v50
	v_and_b32_e32 v50, 0xffff0000, v50
	v_lshlrev_b32_e32 v54, 16, v51
	v_and_b32_e32 v51, 0xffff0000, v51
	v_lshlrev_b32_e32 v55, 16, v52
	v_and_b32_e32 v52, 0xffff0000, v52
	v_lshlrev_b32_e32 v57, 16, v53
	v_and_b32_e32 v53, 0xffff0000, v53
	v_add_f32_e32 v41, v41, v49
	v_add_f32_e32 v42, v42, v50
	v_add_f32_e32 v43, v43, v54
	v_add_f32_e32 v44, v44, v51
	v_add_f32_e32 v45, v45, v55
	v_add_f32_e32 v46, v46, v52
	v_add_f32_e32 v47, v47, v57
	v_add_f32_e32 v48, v48, v53
	v_fma_f32 v32, v40, v41, -v32
	v_fma_f32 v33, v40, v42, -v33
	v_fma_f32 v34, v40, v43, -v34
	v_fma_f32 v35, v40, v44, -v35
	v_fma_f32 v36, v40, v45, -v36
	v_fma_f32 v37, v40, v46, -v37
	v_fma_f32 v38, v40, v47, -v38
	v_fma_f32 v39, v40, v48, -v39
	v_cvt_pk_bf16_f32 v42, v32, v33
	v_cvt_pk_bf16_f32 v43, v34, v35
	v_cvt_pk_bf16_f32 v44, v36, v37
	v_cvt_pk_bf16_f32 v45, v38, v39
	s_waitcnt vmcnt(3)
	s_nop 0
	v_mfma_f32_16x16x32_bf16 v[32:35], v[90:93], v[42:45], 0
	s_waitcnt vmcnt(2)
	v_mfma_f32_16x16x32_bf16 v[36:39], v[94:97], v[42:45], 0
	s_waitcnt vmcnt(1)
	v_mfma_f32_16x16x32_bf16 v[48:51], v[106:109], v[42:45], 0
	s_waitcnt vmcnt(0)
	v_mfma_f32_16x16x32_bf16 v[52:55], v[110:113], v[42:45], 0
	global_load_dwordx4 v[90:93], v[114:115], off
	global_load_dwordx4 v[94:97], v[116:117], off
	global_load_dwordx4 v[106:109], v[118:119], off
	global_load_dwordx4 v[110:113], v[120:121], off
	ds_read_b128 v[42:45], v149 offset:2432
	s_waitcnt lgkmcnt(0)
	v_lshlrev_b32_e32 v41, 16, v42
	v_and_b32_e32 v42, 0xffff0000, v42
	v_lshlrev_b32_e32 v46, 16, v43
	v_and_b32_e32 v43, 0xffff0000, v43
	v_lshlrev_b32_e32 v47, 16, v44
	v_and_b32_e32 v44, 0xffff0000, v44
	v_lshlrev_b32_e32 v57, 16, v45
	v_and_b32_e32 v45, 0xffff0000, v45
	v_add_f32_e32 v58, 0, v42
	v_add_f32_e32 v59, 0, v43
	v_add_f32_e32 v60, 0, v44
	v_add_f32_e32 v61, 0, v45
	ds_read_b128 v[42:45], v149 offset:2960
	v_add_f32_e32 v41, 0, v41
	v_add_f32_e32 v46, 0, v46
	v_add_f32_e32 v47, 0, v47
	v_add_f32_e32 v57, 0, v57
	s_waitcnt lgkmcnt(0)
	v_lshlrev_b32_e32 v62, 16, v42
	v_and_b32_e32 v42, 0xffff0000, v42
	v_lshlrev_b32_e32 v63, 16, v43
	v_and_b32_e32 v43, 0xffff0000, v43
	v_lshlrev_b32_e32 v64, 16, v44
	v_and_b32_e32 v44, 0xffff0000, v44
	v_lshlrev_b32_e32 v65, 16, v45
	v_and_b32_e32 v45, 0xffff0000, v45
	v_add_f32_e32 v58, v58, v42
	v_add_f32_e32 v59, v59, v43
	v_add_f32_e32 v60, v60, v44
	v_add_f32_e32 v61, v61, v45
	ds_read_b128 v[42:45], v149 offset:3488
	v_add_f32_e32 v41, v41, v62
	v_add_f32_e32 v46, v46, v63
	v_add_f32_e32 v47, v47, v64
	v_add_f32_e32 v57, v57, v65
	s_waitcnt lgkmcnt(0)
	v_lshlrev_b32_e32 v62, 16, v42
	v_and_b32_e32 v42, 0xffff0000, v42
	v_lshlrev_b32_e32 v63, 16, v43
	v_and_b32_e32 v43, 0xffff0000, v43
	v_lshlrev_b32_e32 v64, 16, v44
	v_and_b32_e32 v44, 0xffff0000, v44
	v_lshlrev_b32_e32 v65, 16, v45
	v_and_b32_e32 v45, 0xffff0000, v45
	v_add_f32_e32 v58, v58, v42
	v_add_f32_e32 v59, v59, v43
	v_add_f32_e32 v60, v60, v44
	v_add_f32_e32 v61, v61, v45
	ds_read_b128 v[42:45], v149 offset:4016
	v_add_f32_e32 v41, v41, v62
	v_add_f32_e32 v46, v46, v63
	v_add_f32_e32 v47, v47, v64
	v_add_f32_e32 v57, v57, v65
	s_waitcnt lgkmcnt(0)
	v_lshlrev_b32_e32 v62, 16, v42
	v_and_b32_e32 v42, 0xffff0000, v42
	v_lshlrev_b32_e32 v63, 16, v43
	v_and_b32_e32 v43, 0xffff0000, v43
	v_lshlrev_b32_e32 v64, 16, v44
	v_and_b32_e32 v44, 0xffff0000, v44
	v_lshlrev_b32_e32 v65, 16, v45
	v_and_b32_e32 v45, 0xffff0000, v45
	v_add_f32_e32 v66, v58, v42
	v_add_f32_e32 v67, v59, v43
	v_add_f32_e32 v68, v60, v44
	v_add_f32_e32 v69, v61, v45
	ds_read_b128 v[58:61], v149 offset:4544
	v_add_f32_e32 v62, v41, v62
	v_add_f32_e32 v63, v46, v63
	v_add_f32_e32 v64, v47, v64
	v_add_f32_e32 v65, v57, v65
	s_waitcnt lgkmcnt(0)
	v_lshlrev_b32_e32 v41, 16, v58
	v_and_b32_e32 v42, 0xffff0000, v58
	v_lshlrev_b32_e32 v43, 16, v59
	v_and_b32_e32 v44, 0xffff0000, v59
	v_lshlrev_b32_e32 v45, 16, v60
	v_and_b32_e32 v46, 0xffff0000, v60
	v_lshlrev_b32_e32 v47, 16, v61
	v_and_b32_e32 v57, 0xffff0000, v61
	ds_read_b128 v[58:61], v149 offset:5072
	v_add_f32_e32 v66, v66, v42
	v_add_f32_e32 v67, v67, v44
	v_add_f32_e32 v68, v68, v46
	v_add_f32_e32 v69, v69, v57
	s_waitcnt lgkmcnt(0)
	v_lshlrev_b32_e32 v70, 16, v58
	v_and_b32_e32 v58, 0xffff0000, v58
	v_lshlrev_b32_e32 v71, 16, v59
	v_and_b32_e32 v59, 0xffff0000, v59
	v_lshlrev_b32_e32 v131, 16, v60
	v_and_b32_e32 v60, 0xffff0000, v60
	v_lshlrev_b32_e32 v133, 16, v61
	v_and_b32_e32 v61, 0xffff0000, v61
	v_add_f32_e32 v66, v66, v58
	v_add_f32_e32 v67, v67, v59
	v_add_f32_e32 v68, v68, v60
	v_add_f32_e32 v69, v69, v61
	ds_read_b128 v[58:61], v149 offset:5600
	v_add_f32_e32 v62, v62, v41
	v_add_f32_e32 v63, v63, v43
	v_add_f32_e32 v64, v64, v45
	v_add_f32_e32 v65, v65, v47
	v_add_f32_e32 v62, v62, v70
	v_add_f32_e32 v63, v63, v71
	v_add_f32_e32 v64, v64, v131
	v_add_f32_e32 v65, v65, v133
	s_waitcnt lgkmcnt(0)
	v_lshlrev_b32_e32 v70, 16, v58
	v_and_b32_e32 v71, 0xffff0000, v58
	v_lshlrev_b32_e32 v131, 16, v59
	v_and_b32_e32 v133, 0xffff0000, v59
	v_lshlrev_b32_e32 v151, 16, v60
	v_and_b32_e32 v152, 0xffff0000, v60
	v_lshlrev_b32_e32 v153, 16, v61
	v_and_b32_e32 v154, 0xffff0000, v61
	v_add_f32_e32 v58, v62, v70
	v_add_f32_e32 v59, v66, v71
	v_add_f32_e32 v60, v63, v131
	v_add_f32_e32 v61, v67, v133
	v_add_f32_e32 v62, v64, v151
	v_add_f32_e32 v63, v68, v152
	v_add_f32_e32 v64, v65, v153
	v_add_f32_e32 v65, v69, v154
	ds_read_b128 v[66:69], v149 offset:6128
	s_waitcnt lgkmcnt(0)
	v_lshlrev_b32_e32 v70, 16, v66
	v_and_b32_e32 v66, 0xffff0000, v66
	v_lshlrev_b32_e32 v71, 16, v67
	v_and_b32_e32 v67, 0xffff0000, v67
	v_lshlrev_b32_e32 v131, 16, v68
	v_and_b32_e32 v68, 0xffff0000, v68
	v_lshlrev_b32_e32 v133, 16, v69
	v_and_b32_e32 v69, 0xffff0000, v69
	v_add_f32_e32 v58, v58, v70
	v_add_f32_e32 v59, v59, v66
	v_add_f32_e32 v60, v60, v71
	v_add_f32_e32 v61, v61, v67
	v_add_f32_e32 v62, v62, v131
	v_add_f32_e32 v63, v63, v68
	v_add_f32_e32 v64, v64, v133
	v_add_f32_e32 v65, v65, v69
	v_fma_f32 v41, v40, v58, -v41
	v_fma_f32 v42, v40, v59, -v42
	v_fma_f32 v43, v40, v60, -v43
	v_fma_f32 v44, v40, v61, -v44
	v_fma_f32 v45, v40, v62, -v45
	v_fma_f32 v46, v40, v63, -v46
	v_fma_f32 v47, v40, v64, -v47
	v_fma_f32 v40, v40, v65, -v57
	v_cvt_pk_bf16_f32 v58, v41, v42
	v_cvt_pk_bf16_f32 v59, v43, v44
	v_cvt_pk_bf16_f32 v60, v45, v46
	v_cvt_pk_bf16_f32 v61, v47, v40
	s_waitcnt vmcnt(0)
	s_nop 0
	v_mfma_f32_16x16x32_bf16 v[44:47], v[198:201], v[58:61], v[32:35]
	s_nop 2
	s_waitcnt vmcnt(0)
	v_mfma_f32_16x16x32_bf16 v[40:43], v[202:205], v[58:61], v[36:39]
	s_waitcnt vmcnt(0)
	v_mfma_f32_16x16x32_bf16 v[36:39], v[214:217], v[58:61], v[48:51]
	s_nop 1
	v_max_i32_e32 v48, 8, v56
	v_min_i32_e32 v49, 0x1ff8, v56
	v_sub_u32_e32 v48, v49, v48
	v_add_u32_e32 v48, 16, v48
	v_cvt_f32_i32_e32 v48, v48
	s_waitcnt vmcnt(0)
	v_mfma_f32_16x16x32_bf16 v[32:35], v[218:221], v[58:61], v[52:55]
	v_div_scale_f32 v49, s[18:19], v48, v48, 1.0
	v_rcp_f32_e32 v50, v49
	s_mov_b64 s[18:19], 0x1a000200
	v_fma_f32 v51, -v49, v50, 1.0
	v_fmac_f32_e32 v50, v51, v50
	v_div_scale_f32 v51, vcc, 1.0, v48, 1.0
	v_mul_f32_e32 v52, v51, v50
	v_fma_f32 v53, -v49, v52, v51
	v_fmac_f32_e32 v52, v53, v50
	v_fma_f32 v49, -v49, v52, v51
	v_div_fmas_f32 v49, v49, v50, v52
	v_div_fixup_f32 v56, v49, v48, 1.0
	ds_read_b128 v[48:51], v149 offset:384
	s_waitcnt lgkmcnt(0)
	v_lshlrev_b32_e32 v52, 16, v48
	v_and_b32_e32 v48, 0xffff0000, v48
	v_lshlrev_b32_e32 v53, 16, v49
	v_and_b32_e32 v49, 0xffff0000, v49
	v_lshlrev_b32_e32 v54, 16, v50
	v_and_b32_e32 v50, 0xffff0000, v50
	v_lshlrev_b32_e32 v55, 16, v51
	v_and_b32_e32 v51, 0xffff0000, v51
	v_add_f32_e32 v57, 0, v48
	v_add_f32_e32 v58, 0, v49
	v_add_f32_e32 v59, 0, v50
	v_add_f32_e32 v60, 0, v51
	ds_read_b128 v[48:51], v149 offset:912
	v_add_f32_e32 v52, 0, v52
	v_add_f32_e32 v53, 0, v53
	v_add_f32_e32 v54, 0, v54
	v_add_f32_e32 v55, 0, v55
	s_waitcnt lgkmcnt(0)
	v_lshlrev_b32_e32 v61, 16, v48
	v_and_b32_e32 v48, 0xffff0000, v48
	v_lshlrev_b32_e32 v62, 16, v49
	v_and_b32_e32 v49, 0xffff0000, v49
	v_lshlrev_b32_e32 v63, 16, v50
	v_and_b32_e32 v50, 0xffff0000, v50
	v_lshlrev_b32_e32 v64, 16, v51
	v_and_b32_e32 v51, 0xffff0000, v51
	v_add_f32_e32 v57, v57, v48
	v_add_f32_e32 v58, v58, v49
	v_add_f32_e32 v59, v59, v50
	v_add_f32_e32 v60, v60, v51
	ds_read_b128 v[48:51], v149 offset:1440
	v_add_f32_e32 v52, v52, v61
	v_add_f32_e32 v53, v53, v62
	v_add_f32_e32 v54, v54, v63
	v_add_f32_e32 v55, v55, v64
	s_waitcnt lgkmcnt(0)
	v_lshlrev_b32_e32 v61, 16, v48
	v_and_b32_e32 v48, 0xffff0000, v48
	v_lshlrev_b32_e32 v62, 16, v49
	v_and_b32_e32 v49, 0xffff0000, v49
	v_lshlrev_b32_e32 v63, 16, v50
	v_and_b32_e32 v50, 0xffff0000, v50
	v_lshlrev_b32_e32 v64, 16, v51
	v_and_b32_e32 v51, 0xffff0000, v51
	v_add_f32_e32 v57, v57, v48
	v_add_f32_e32 v58, v58, v49
	v_add_f32_e32 v59, v59, v50
	v_add_f32_e32 v60, v60, v51
	ds_read_b128 v[48:51], v149 offset:1968
	v_add_f32_e32 v52, v52, v61
	v_add_f32_e32 v53, v53, v62
	v_add_f32_e32 v54, v54, v63
	v_add_f32_e32 v55, v55, v64
	s_waitcnt lgkmcnt(0)
	v_lshlrev_b32_e32 v61, 16, v48
	v_and_b32_e32 v48, 0xffff0000, v48
	v_lshlrev_b32_e32 v62, 16, v49
	v_and_b32_e32 v49, 0xffff0000, v49
	v_lshlrev_b32_e32 v63, 16, v50
	v_and_b32_e32 v50, 0xffff0000, v50
	v_lshlrev_b32_e32 v64, 16, v51
	v_and_b32_e32 v51, 0xffff0000, v51
	v_add_f32_e32 v57, v57, v48
	v_add_f32_e32 v58, v58, v49
	v_add_f32_e32 v59, v59, v50
	v_add_f32_e32 v60, v60, v51
	ds_read_b128 v[48:51], v149 offset:2496
	v_add_f32_e32 v52, v52, v61
	v_add_f32_e32 v53, v53, v62
	v_add_f32_e32 v54, v54, v63
	v_add_f32_e32 v55, v55, v64
	s_waitcnt lgkmcnt(0)
	v_lshlrev_b32_e32 v61, 16, v48
	v_and_b32_e32 v48, 0xffff0000, v48
	v_lshlrev_b32_e32 v62, 16, v49
	v_and_b32_e32 v49, 0xffff0000, v49
	v_lshlrev_b32_e32 v63, 16, v50
	v_and_b32_e32 v50, 0xffff0000, v50
	v_lshlrev_b32_e32 v64, 16, v51
	v_and_b32_e32 v51, 0xffff0000, v51
	v_add_f32_e32 v57, v57, v48
	v_add_f32_e32 v58, v58, v49
	v_add_f32_e32 v59, v59, v50
	v_add_f32_e32 v60, v60, v51
	ds_read_b128 v[48:51], v149 offset:3024
	v_add_f32_e32 v52, v52, v61
	v_add_f32_e32 v53, v53, v62
	v_add_f32_e32 v54, v54, v63
	v_add_f32_e32 v55, v55, v64
	s_waitcnt lgkmcnt(0)
	v_lshlrev_b32_e32 v61, 16, v48
	v_and_b32_e32 v48, 0xffff0000, v48
	v_lshlrev_b32_e32 v62, 16, v49
	v_and_b32_e32 v49, 0xffff0000, v49
	v_lshlrev_b32_e32 v63, 16, v50
	v_and_b32_e32 v50, 0xffff0000, v50
	v_lshlrev_b32_e32 v64, 16, v51
	v_and_b32_e32 v51, 0xffff0000, v51
	v_add_f32_e32 v57, v57, v48
	v_add_f32_e32 v58, v58, v49
	v_add_f32_e32 v59, v59, v50
	v_add_f32_e32 v60, v60, v51
	ds_read_b128 v[48:51], v149 offset:3552
	v_add_f32_e32 v52, v52, v61
	v_add_f32_e32 v53, v53, v62
	v_add_f32_e32 v54, v54, v63
	v_add_f32_e32 v55, v55, v64
	s_waitcnt lgkmcnt(0)
	v_lshlrev_b32_e32 v61, 16, v48
	v_and_b32_e32 v48, 0xffff0000, v48
	v_lshlrev_b32_e32 v62, 16, v49
	v_and_b32_e32 v49, 0xffff0000, v49
	v_lshlrev_b32_e32 v63, 16, v50
	v_and_b32_e32 v50, 0xffff0000, v50
	v_lshlrev_b32_e32 v64, 16, v51
	v_and_b32_e32 v51, 0xffff0000, v51
	v_add_f32_e32 v57, v57, v48
	v_add_f32_e32 v58, v58, v49
	v_add_f32_e32 v59, v59, v50
	v_add_f32_e32 v60, v60, v51
	ds_read_b128 v[48:51], v149 offset:4080
	v_add_f32_e32 v52, v52, v61
	v_add_f32_e32 v53, v53, v62
	v_add_f32_e32 v54, v54, v63
	v_add_f32_e32 v55, v55, v64
	s_waitcnt lgkmcnt(0)
	v_lshlrev_b32_e32 v61, 16, v48
	v_lshlrev_b32_e32 v62, 16, v49
	v_lshlrev_b32_e32 v63, 16, v50
	v_lshlrev_b32_e32 v64, 16, v51
	v_add_f32_e32 v61, v52, v61
	v_add_f32_e32 v62, v53, v62
	v_add_f32_e32 v63, v54, v63
	v_add_f32_e32 v64, v55, v64
	ds_read_b128 v[52:55], v149 offset:4608
	v_and_b32_e32 v48, 0xffff0000, v48
	v_and_b32_e32 v49, 0xffff0000, v49
	v_and_b32_e32 v50, 0xffff0000, v50
	v_and_b32_e32 v51, 0xffff0000, v51
	v_add_f32_e32 v57, v57, v48
	v_add_f32_e32 v58, v58, v49
	v_add_f32_e32 v59, v59, v50
	v_add_f32_e32 v60, v60, v51
	s_waitcnt lgkmcnt(0)
	v_lshlrev_b32_e32 v48, 16, v52
	v_and_b32_e32 v49, 0xffff0000, v52
	v_lshlrev_b32_e32 v50, 16, v53
	v_and_b32_e32 v51, 0xffff0000, v53
	v_lshlrev_b32_e32 v52, 16, v54
	v_and_b32_e32 v53, 0xffff0000, v54
	v_lshlrev_b32_e32 v54, 16, v55
	v_and_b32_e32 v55, 0xffff0000, v55
	v_add_f32_e32 v65, v61, v48
	v_add_f32_e32 v66, v58, v51
	v_add_f32_e32 v67, v59, v53
	v_add_f32_e32 v68, v60, v55
	ds_read_b128 v[58:61], v149 offset:5136
	v_add_f32_e32 v57, v57, v49
	v_add_f32_e32 v62, v62, v50
	v_add_f32_e32 v63, v63, v52
	v_add_f32_e32 v64, v64, v54
	s_waitcnt lgkmcnt(0)
	v_lshlrev_b32_e32 v69, 16, v58
	v_and_b32_e32 v58, 0xffff0000, v58
	v_lshlrev_b32_e32 v70, 16, v59
	v_and_b32_e32 v59, 0xffff0000, v59
	v_lshlrev_b32_e32 v71, 16, v60
	v_and_b32_e32 v60, 0xffff0000, v60
	v_lshlrev_b32_e32 v131, 16, v61
	v_and_b32_e32 v61, 0xffff0000, v61
	v_add_f32_e32 v57, v57, v58
	v_add_f32_e32 v66, v66, v59
	v_add_f32_e32 v67, v67, v60
	v_add_f32_e32 v68, v68, v61
	ds_read_b128 v[58:61], v149 offset:5664
	v_add_f32_e32 v65, v65, v69
	v_add_f32_e32 v62, v62, v70
	v_add_f32_e32 v63, v63, v71
	v_add_f32_e32 v64, v64, v131
	s_waitcnt lgkmcnt(0)
	v_lshlrev_b32_e32 v69, 16, v58
	v_and_b32_e32 v58, 0xffff0000, v58
	v_lshlrev_b32_e32 v70, 16, v59
	v_and_b32_e32 v59, 0xffff0000, v59
	v_lshlrev_b32_e32 v71, 16, v60
	v_and_b32_e32 v60, 0xffff0000, v60
	v_lshlrev_b32_e32 v131, 16, v61
	v_and_b32_e32 v61, 0xffff0000, v61
	v_add_f32_e32 v57, v57, v58
	v_add_f32_e32 v66, v66, v59
	v_add_f32_e32 v67, v67, v60
	v_add_f32_e32 v68, v68, v61
	ds_read_b128 v[58:61], v149 offset:6192
	v_add_f32_e32 v65, v65, v69
	v_add_f32_e32 v62, v62, v70
	v_add_f32_e32 v63, v63, v71
	v_add_f32_e32 v64, v64, v131
	s_waitcnt lgkmcnt(0)
	v_lshlrev_b32_e32 v69, 16, v58
	v_and_b32_e32 v58, 0xffff0000, v58
	v_lshlrev_b32_e32 v70, 16, v59
	v_and_b32_e32 v59, 0xffff0000, v59
	v_lshlrev_b32_e32 v71, 16, v60
	v_and_b32_e32 v60, 0xffff0000, v60
	v_lshlrev_b32_e32 v131, 16, v61
	v_and_b32_e32 v61, 0xffff0000, v61
	v_add_f32_e32 v57, v57, v58
	v_add_f32_e32 v66, v66, v59
	v_add_f32_e32 v67, v67, v60
	v_add_f32_e32 v68, v68, v61
	ds_read_b128 v[58:61], v149 offset:6720
	v_add_f32_e32 v65, v65, v69
	v_add_f32_e32 v62, v62, v70
	v_add_f32_e32 v63, v63, v71
	v_add_f32_e32 v64, v64, v131
	s_waitcnt lgkmcnt(0)
	v_lshlrev_b32_e32 v69, 16, v58
	v_and_b32_e32 v58, 0xffff0000, v58
	v_lshlrev_b32_e32 v70, 16, v59
	v_and_b32_e32 v59, 0xffff0000, v59
	v_lshlrev_b32_e32 v71, 16, v60
	v_and_b32_e32 v60, 0xffff0000, v60
	v_lshlrev_b32_e32 v131, 16, v61
	v_and_b32_e32 v61, 0xffff0000, v61
	v_add_f32_e32 v57, v57, v58
	v_add_f32_e32 v66, v66, v59
	v_add_f32_e32 v67, v67, v60
	v_add_f32_e32 v68, v68, v61
	ds_read_b128 v[58:61], v149 offset:7248
	v_add_f32_e32 v65, v65, v69
	v_add_f32_e32 v62, v62, v70
	v_add_f32_e32 v63, v63, v71
	v_add_f32_e32 v64, v64, v131
	s_waitcnt lgkmcnt(0)
	v_lshlrev_b32_e32 v69, 16, v58
	v_and_b32_e32 v58, 0xffff0000, v58
	v_lshlrev_b32_e32 v70, 16, v59
	v_and_b32_e32 v59, 0xffff0000, v59
	v_lshlrev_b32_e32 v71, 16, v60
	v_and_b32_e32 v60, 0xffff0000, v60
	v_lshlrev_b32_e32 v131, 16, v61
	v_and_b32_e32 v61, 0xffff0000, v61
	v_add_f32_e32 v65, v65, v69
	v_add_f32_e32 v69, v57, v58
	v_add_f32_e32 v66, v66, v59
	v_add_f32_e32 v67, v67, v60
	v_add_f32_e32 v68, v68, v61
	ds_read_b128 v[58:61], v149 offset:7776
	v_add_f32_e32 v63, v63, v71
	v_add_f32_e32 v64, v64, v131
	v_add_f32_e32 v62, v62, v70
	s_waitcnt lgkmcnt(0)
	v_lshlrev_b32_e32 v131, 16, v60
	v_lshlrev_b32_e32 v151, 16, v61
	v_and_b32_e32 v152, 0xffff0000, v61
	v_add_f32_e32 v61, v63, v131
	v_add_f32_e32 v63, v64, v151
	v_add_f32_e32 v64, v68, v152
	ds_read_b128 v[152:155], v149 offset:8304
	v_lshlrev_b32_e32 v57, 16, v58
	v_and_b32_e32 v58, 0xffff0000, v58
	v_lshlrev_b32_e32 v70, 16, v59
	v_and_b32_e32 v71, 0xffff0000, v59
	v_and_b32_e32 v133, 0xffff0000, v60
	v_add_f32_e32 v57, v65, v57
	v_add_f32_e32 v58, v69, v58
	v_add_f32_e32 v59, v62, v70
	v_add_f32_e32 v60, v66, v71
	v_add_f32_e32 v62, v67, v133
	s_waitcnt lgkmcnt(0)
	v_lshlrev_b32_e32 v65, 16, v152
	v_and_b32_e32 v66, 0xffff0000, v152
	v_lshlrev_b32_e32 v67, 16, v153
	v_and_b32_e32 v68, 0xffff0000, v153
	v_lshlrev_b32_e32 v69, 16, v154
	v_and_b32_e32 v70, 0xffff0000, v154
	v_lshlrev_b32_e32 v71, 16, v155
	v_and_b32_e32 v131, 0xffff0000, v155
	v_add_f32_e32 v57, v57, v65
	v_add_f32_e32 v58, v58, v66
	v_add_f32_e32 v59, v59, v67
	v_add_f32_e32 v60, v60, v68
	v_add_f32_e32 v61, v61, v69
	v_add_f32_e32 v62, v62, v70
	v_add_f32_e32 v63, v63, v71
	v_add_f32_e32 v64, v64, v131
	v_fma_f32 v48, v56, v57, -v48
	v_fma_f32 v49, v56, v58, -v49
	v_fma_f32 v50, v56, v59, -v50
	v_fma_f32 v51, v56, v60, -v51
	v_fma_f32 v52, v56, v61, -v52
	v_fma_f32 v53, v56, v62, -v53
	v_fma_f32 v54, v56, v63, -v54
	v_fma_f32 v55, v56, v64, -v55
	v_cvt_pk_bf16_f32 v58, v48, v49
	v_cvt_pk_bf16_f32 v59, v50, v51
	v_cvt_pk_bf16_f32 v60, v52, v53
	v_cvt_pk_bf16_f32 v61, v54, v55
	s_waitcnt vmcnt(3)
	s_nop 0
	v_mfma_f32_16x16x32_bf16 v[48:51], v[90:93], v[58:61], 0
	s_waitcnt vmcnt(2)
	v_mfma_f32_16x16x32_bf16 v[52:55], v[94:97], v[58:61], 0
	s_waitcnt vmcnt(1)
	v_mfma_f32_16x16x32_bf16 v[64:67], v[106:109], v[58:61], 0
	s_waitcnt vmcnt(0)
	v_mfma_f32_16x16x32_bf16 v[68:71], v[110:113], v[58:61], 0
	ds_read_b128 v[58:61], v149 offset:448
	s_waitcnt lgkmcnt(0)
	v_lshlrev_b32_e32 v57, 16, v58
	v_and_b32_e32 v58, 0xffff0000, v58
	v_lshlrev_b32_e32 v62, 16, v59
	v_and_b32_e32 v59, 0xffff0000, v59
	v_lshlrev_b32_e32 v63, 16, v60
	v_and_b32_e32 v60, 0xffff0000, v60
	v_lshlrev_b32_e32 v131, 16, v61
	v_and_b32_e32 v61, 0xffff0000, v61
	v_add_f32_e32 v133, 0, v58
	v_add_f32_e32 v151, 0, v59
	v_add_f32_e32 v152, 0, v60
	v_add_f32_e32 v153, 0, v61
	ds_read_b128 v[58:61], v149 offset:976
	v_add_f32_e32 v57, 0, v57
	v_add_f32_e32 v62, 0, v62
	v_add_f32_e32 v63, 0, v63
	v_add_f32_e32 v131, 0, v131
	s_waitcnt lgkmcnt(0)
	v_lshlrev_b32_e32 v154, 16, v58
	v_and_b32_e32 v58, 0xffff0000, v58
	v_lshlrev_b32_e32 v155, 16, v59
	v_and_b32_e32 v59, 0xffff0000, v59
	v_lshlrev_b32_e32 v156, 16, v60
	v_and_b32_e32 v60, 0xffff0000, v60
	v_lshlrev_b32_e32 v157, 16, v61
	v_and_b32_e32 v61, 0xffff0000, v61
	v_add_f32_e32 v133, v133, v58
	v_add_f32_e32 v151, v151, v59
	v_add_f32_e32 v152, v152, v60
	v_add_f32_e32 v153, v153, v61
	ds_read_b128 v[58:61], v149 offset:1504
	v_add_f32_e32 v57, v57, v154
	v_add_f32_e32 v62, v62, v155
	v_add_f32_e32 v63, v63, v156
	v_add_f32_e32 v131, v131, v157
	s_waitcnt lgkmcnt(0)
	v_lshlrev_b32_e32 v154, 16, v58
	v_and_b32_e32 v58, 0xffff0000, v58
	v_lshlrev_b32_e32 v155, 16, v59
	v_and_b32_e32 v59, 0xffff0000, v59
	v_lshlrev_b32_e32 v156, 16, v60
	v_and_b32_e32 v60, 0xffff0000, v60
	v_lshlrev_b32_e32 v157, 16, v61
	v_and_b32_e32 v61, 0xffff0000, v61
	v_add_f32_e32 v133, v133, v58
	v_add_f32_e32 v151, v151, v59
	v_add_f32_e32 v152, v152, v60
	v_add_f32_e32 v153, v153, v61
	ds_read_b128 v[58:61], v149 offset:2032
	v_add_f32_e32 v57, v57, v154
	v_add_f32_e32 v62, v62, v155
	v_add_f32_e32 v63, v63, v156
	v_add_f32_e32 v131, v131, v157
	s_waitcnt lgkmcnt(0)
	v_lshlrev_b32_e32 v154, 16, v58
	v_and_b32_e32 v58, 0xffff0000, v58
	v_lshlrev_b32_e32 v155, 16, v59
	v_and_b32_e32 v59, 0xffff0000, v59
	v_lshlrev_b32_e32 v156, 16, v60
	v_and_b32_e32 v60, 0xffff0000, v60
	v_lshlrev_b32_e32 v157, 16, v61
	v_and_b32_e32 v61, 0xffff0000, v61
	v_add_f32_e32 v133, v133, v58
	v_add_f32_e32 v151, v151, v59
	v_add_f32_e32 v152, v152, v60
	v_add_f32_e32 v153, v153, v61
	ds_read_b128 v[58:61], v149 offset:2560
	v_add_f32_e32 v57, v57, v154
	v_add_f32_e32 v62, v62, v155
	v_add_f32_e32 v63, v63, v156
	v_add_f32_e32 v131, v131, v157
	s_waitcnt lgkmcnt(0)
	v_lshlrev_b32_e32 v154, 16, v58
	v_and_b32_e32 v58, 0xffff0000, v58
	v_lshlrev_b32_e32 v155, 16, v59
	v_and_b32_e32 v59, 0xffff0000, v59
	v_lshlrev_b32_e32 v156, 16, v60
	v_and_b32_e32 v60, 0xffff0000, v60
	v_lshlrev_b32_e32 v157, 16, v61
	v_and_b32_e32 v61, 0xffff0000, v61
	v_add_f32_e32 v133, v133, v58
	v_add_f32_e32 v151, v151, v59
	v_add_f32_e32 v152, v152, v60
	v_add_f32_e32 v153, v153, v61
	ds_read_b128 v[58:61], v149 offset:3088
	v_add_f32_e32 v57, v57, v154
	v_add_f32_e32 v62, v62, v155
	v_add_f32_e32 v63, v63, v156
	v_add_f32_e32 v131, v131, v157
	s_waitcnt lgkmcnt(0)
	v_lshlrev_b32_e32 v154, 16, v58
	v_and_b32_e32 v58, 0xffff0000, v58
	v_lshlrev_b32_e32 v155, 16, v59
	v_and_b32_e32 v59, 0xffff0000, v59
	v_lshlrev_b32_e32 v156, 16, v60
	v_and_b32_e32 v60, 0xffff0000, v60
	v_lshlrev_b32_e32 v157, 16, v61
	v_and_b32_e32 v61, 0xffff0000, v61
	v_add_f32_e32 v133, v133, v58
	v_add_f32_e32 v151, v151, v59
	v_add_f32_e32 v152, v152, v60
	v_add_f32_e32 v153, v153, v61
	ds_read_b128 v[58:61], v149 offset:3616
	v_add_f32_e32 v57, v57, v154
	v_add_f32_e32 v62, v62, v155
	v_add_f32_e32 v63, v63, v156
	v_add_f32_e32 v131, v131, v157
	s_waitcnt lgkmcnt(0)
	v_lshlrev_b32_e32 v154, 16, v58
	v_and_b32_e32 v58, 0xffff0000, v58
	v_lshlrev_b32_e32 v155, 16, v59
	v_and_b32_e32 v59, 0xffff0000, v59
	v_lshlrev_b32_e32 v156, 16, v60
	v_and_b32_e32 v60, 0xffff0000, v60
	v_lshlrev_b32_e32 v157, 16, v61
	v_and_b32_e32 v61, 0xffff0000, v61
	v_add_f32_e32 v133, v133, v58
	v_add_f32_e32 v151, v151, v59
	v_add_f32_e32 v152, v152, v60
	v_add_f32_e32 v153, v153, v61
	ds_read_b128 v[58:61], v149 offset:4144
	v_add_f32_e32 v57, v57, v154
	v_add_f32_e32 v62, v62, v155
	v_add_f32_e32 v63, v63, v156
	v_add_f32_e32 v131, v131, v157
	s_waitcnt lgkmcnt(0)
	v_lshlrev_b32_e32 v154, 16, v58
	v_lshlrev_b32_e32 v155, 16, v59
	v_lshlrev_b32_e32 v156, 16, v60
	v_and_b32_e32 v60, 0xffff0000, v60
	v_lshlrev_b32_e32 v157, 16, v61
	v_and_b32_e32 v61, 0xffff0000, v61
	v_add_f32_e32 v158, v57, v154
	v_add_f32_e32 v159, v62, v155
	v_add_f32_e32 v160, v152, v60
	v_add_f32_e32 v161, v153, v61
	ds_read_b128 v[152:155], v149 offset:4672
	v_and_b32_e32 v58, 0xffff0000, v58
	v_and_b32_e32 v59, 0xffff0000, v59
	v_add_f32_e32 v133, v133, v58
	v_add_f32_e32 v151, v151, v59
	v_add_f32_e32 v156, v63, v156
	v_add_f32_e32 v157, v131, v157
	s_waitcnt lgkmcnt(0)
	v_lshlrev_b32_e32 v57, 16, v152
	v_and_b32_e32 v58, 0xffff0000, v152
	v_lshlrev_b32_e32 v59, 16, v153
	v_and_b32_e32 v60, 0xffff0000, v153
	v_lshlrev_b32_e32 v61, 16, v154
	v_and_b32_e32 v62, 0xffff0000, v154
	v_lshlrev_b32_e32 v63, 16, v155
	v_and_b32_e32 v131, 0xffff0000, v155
	ds_read_b128 v[152:155], v149 offset:5200
	v_add_f32_e32 v133, v133, v58
	v_add_f32_e32 v151, v151, v60
	v_add_f32_e32 v160, v160, v62
	v_add_f32_e32 v161, v161, v131
	s_waitcnt lgkmcnt(0)
	v_lshlrev_b32_e32 v162, 16, v152
	v_and_b32_e32 v152, 0xffff0000, v152
	v_lshlrev_b32_e32 v163, 16, v153
	v_and_b32_e32 v153, 0xffff0000, v153
	v_lshlrev_b32_e32 v164, 16, v154
	v_and_b32_e32 v154, 0xffff0000, v154
	v_lshlrev_b32_e32 v165, 16, v155
	v_and_b32_e32 v155, 0xffff0000, v155
	v_add_f32_e32 v133, v133, v152
	v_add_f32_e32 v151, v151, v153
	v_add_f32_e32 v160, v160, v154
	v_add_f32_e32 v161, v161, v155
	ds_read_b128 v[152:155], v149 offset:5728
	v_add_f32_e32 v158, v158, v57
	v_add_f32_e32 v159, v159, v59
	v_add_f32_e32 v156, v156, v61
	v_add_f32_e32 v157, v157, v63
	v_add_f32_e32 v158, v158, v162
	v_add_f32_e32 v159, v159, v163
	v_add_f32_e32 v156, v156, v164
	v_add_f32_e32 v157, v157, v165
	s_waitcnt lgkmcnt(0)
	v_lshlrev_b32_e32 v162, 16, v152
	v_and_b32_e32 v152, 0xffff0000, v152
	v_lshlrev_b32_e32 v163, 16, v153
	v_and_b32_e32 v153, 0xffff0000, v153
	v_lshlrev_b32_e32 v164, 16, v154
	v_and_b32_e32 v154, 0xffff0000, v154
	v_lshlrev_b32_e32 v165, 16, v155
	v_and_b32_e32 v155, 0xffff0000, v155
	v_add_f32_e32 v133, v133, v152
	v_add_f32_e32 v151, v151, v153
	v_add_f32_e32 v160, v160, v154
	v_add_f32_e32 v161, v161, v155
	ds_read_b128 v[152:155], v149 offset:6256
	v_add_f32_e32 v158, v158, v162
	v_add_f32_e32 v159, v159, v163
	v_add_f32_e32 v156, v156, v164
	v_add_f32_e32 v157, v157, v165
	s_waitcnt lgkmcnt(0)
	v_lshlrev_b32_e32 v162, 16, v152
	v_and_b32_e32 v152, 0xffff0000, v152
	v_lshlrev_b32_e32 v163, 16, v153
	v_and_b32_e32 v153, 0xffff0000, v153
	v_lshlrev_b32_e32 v164, 16, v154
	v_and_b32_e32 v154, 0xffff0000, v154
	v_lshlrev_b32_e32 v165, 16, v155
	v_and_b32_e32 v155, 0xffff0000, v155
	v_add_f32_e32 v133, v133, v152
	v_add_f32_e32 v151, v151, v153
	v_add_f32_e32 v160, v160, v154
	v_add_f32_e32 v161, v161, v155
	ds_read_b128 v[152:155], v149 offset:6784
	v_add_f32_e32 v158, v158, v162
	v_add_f32_e32 v159, v159, v163
	v_add_f32_e32 v156, v156, v164
	v_add_f32_e32 v157, v157, v165
	s_waitcnt lgkmcnt(0)
	v_lshlrev_b32_e32 v162, 16, v152
	v_and_b32_e32 v152, 0xffff0000, v152
	v_lshlrev_b32_e32 v163, 16, v153
	v_and_b32_e32 v153, 0xffff0000, v153
	v_lshlrev_b32_e32 v164, 16, v154
	v_and_b32_e32 v154, 0xffff0000, v154
	v_lshlrev_b32_e32 v165, 16, v155
	v_and_b32_e32 v155, 0xffff0000, v155
	v_add_f32_e32 v133, v133, v152
	v_add_f32_e32 v151, v151, v153
	v_add_f32_e32 v160, v160, v154
	v_add_f32_e32 v161, v161, v155
	ds_read_b128 v[152:155], v149 offset:7312
	v_add_f32_e32 v158, v158, v162
	v_add_f32_e32 v159, v159, v163
	v_add_f32_e32 v156, v156, v164
	v_add_f32_e32 v157, v157, v165
	s_waitcnt lgkmcnt(0)
	v_lshlrev_b32_e32 v162, 16, v152
	v_and_b32_e32 v152, 0xffff0000, v152
	v_lshlrev_b32_e32 v163, 16, v153
	v_and_b32_e32 v153, 0xffff0000, v153
	v_lshlrev_b32_e32 v164, 16, v154
	v_and_b32_e32 v154, 0xffff0000, v154
	v_lshlrev_b32_e32 v165, 16, v155
	v_and_b32_e32 v155, 0xffff0000, v155
	v_add_f32_e32 v133, v133, v152
	v_add_f32_e32 v151, v151, v153
	v_add_f32_e32 v160, v160, v154
	v_add_f32_e32 v161, v161, v155
	ds_read_b128 v[152:155], v149 offset:7840
	v_add_f32_e32 v158, v158, v162
	v_add_f32_e32 v159, v159, v163
	v_add_f32_e32 v156, v156, v164
	v_add_f32_e32 v157, v157, v165
	s_waitcnt lgkmcnt(0)
	v_lshlrev_b32_e32 v162, 16, v152
	v_and_b32_e32 v152, 0xffff0000, v152
	v_lshlrev_b32_e32 v163, 16, v153
	v_and_b32_e32 v153, 0xffff0000, v153
	v_lshlrev_b32_e32 v164, 16, v154
	v_and_b32_e32 v154, 0xffff0000, v154
	v_lshlrev_b32_e32 v165, 16, v155
	v_and_b32_e32 v155, 0xffff0000, v155
	v_add_f32_e32 v133, v133, v152
	v_add_f32_e32 v151, v151, v153
	v_add_f32_e32 v160, v160, v154
	v_add_f32_e32 v161, v161, v155
	ds_read_b128 v[152:155], v149 offset:8368
	v_add_f32_e32 v158, v158, v162
	v_add_f32_e32 v159, v159, v163
	v_add_f32_e32 v156, v156, v164
	v_add_f32_e32 v157, v157, v165
	s_waitcnt lgkmcnt(0)
	v_lshlrev_b32_e32 v162, 16, v152
	v_and_b32_e32 v152, 0xffff0000, v152
	v_lshlrev_b32_e32 v163, 16, v153
	v_and_b32_e32 v153, 0xffff0000, v153
	v_lshlrev_b32_e32 v164, 16, v154
	v_and_b32_e32 v154, 0xffff0000, v154
	v_lshlrev_b32_e32 v165, 16, v155
	v_and_b32_e32 v155, 0xffff0000, v155
	v_add_f32_e32 v158, v158, v162
	v_add_f32_e32 v133, v133, v152
	v_add_f32_e32 v152, v159, v163
	v_add_f32_e32 v151, v151, v153
	v_add_f32_e32 v153, v156, v164
	v_add_f32_e32 v154, v160, v154
	v_add_f32_e32 v156, v157, v165
	v_add_f32_e32 v155, v161, v155
	v_fma_f32 v57, v56, v158, -v57
	v_fma_f32 v58, v56, v133, -v58
	v_fma_f32 v59, v56, v152, -v59
	v_fma_f32 v60, v56, v151, -v60
	v_fma_f32 v61, v56, v153, -v61
	v_fma_f32 v62, v56, v154, -v62
	v_fma_f32 v63, v56, v156, -v63
	v_fma_f32 v56, v56, v155, -v131
	v_cvt_pk_bf16_f32 v152, v57, v58
	v_cvt_pk_bf16_f32 v153, v59, v60
	v_cvt_pk_bf16_f32 v154, v61, v62
	v_cvt_pk_bf16_f32 v155, v63, v56
	s_waitcnt vmcnt(0)
	s_nop 0
	v_mfma_f32_16x16x32_bf16 v[60:63], v[222:225], v[152:155], v[48:51]
	s_nop 2
	v_mov_b32_e32 v133, v209
	s_waitcnt vmcnt(0)
	v_mfma_f32_16x16x32_bf16 v[56:59], v[226:229], v[152:155], v[52:55]
	s_waitcnt vmcnt(0)
	v_mfma_f32_16x16x32_bf16 v[52:55], v[230:233], v[152:155], v[64:67]
	s_nop 1
	v_pk_mul_f32 v[64:65], v[14:15], v[14:15]
	v_pk_mul_f32 v[66:67], v[12:13], v[12:13]
	s_waitcnt vmcnt(0)
	v_mfma_f32_16x16x32_bf16 v[48:51], v[234:237], v[152:155], v[68:71]
	s_nop 2
	v_pk_mov_b32 v[68:69], v[66:67], v[64:65] op_sel:[1,0]
	v_mov_b32_e32 v67, v65
	v_pk_add_f32 v[64:65], v[68:69], v[66:67]
	v_pk_mul_f32 v[66:67], v[10:11], v[10:11]
	v_pk_mul_f32 v[68:69], v[8:9], v[8:9]
	v_pk_add_f32 v[64:65], v[64:65], v[64:65] op_sel:[0,1] op_sel_hi:[1,0]
	v_pk_mov_b32 v[70:71], v[68:69], v[66:67] op_sel:[1,0]
	v_mov_b32_e32 v69, v67
	v_pk_add_f32 v[66:67], v[70:71], v[68:69]
	v_mul_f32_e32 v68, v0, v0
	v_mul_f32_e32 v69, v1, v1
	v_pk_add_f32 v[66:67], v[66:67], v[66:67] op_sel:[0,1] op_sel_hi:[1,0]
	v_mov_b32_e32 v65, v68
	v_mov_b32_e32 v67, v69
	v_pk_add_f32 v[64:65], v[64:65], v[66:67]
	v_mul_f32_e32 v66, v5, v5
	v_mul_f32_e32 v68, v7, v7
	v_mul_f32_e32 v70, v2, v2
	v_mul_f32_e32 v71, v3, v3
	v_pk_fma_f32 v[66:67], v[4:5], v[4:5], v[66:67] op_sel_hi:[1,1,0]
	v_pk_fma_f32 v[68:69], v[6:7], v[6:7], v[68:69] op_sel_hi:[1,1,0]
	v_mov_b32_e32 v67, v70
	v_mov_b32_e32 v69, v71
	v_pk_add_f32 v[66:67], v[66:67], v[68:69]
	v_pk_mul_f32 v[68:69], v[28:29], v[28:29]
	v_pk_add_f32 v[64:65], v[64:65], v[66:67]
	v_pk_mul_f32 v[66:67], v[30:31], v[30:31]
	v_pk_add_f32 v[64:65], v[64:65], v[64:65] op_sel:[0,1] op_sel_hi:[1,0]
	v_pk_mov_b32 v[70:71], v[68:69], v[66:67] op_sel:[1,0]
	v_mov_b32_e32 v69, v67
	v_pk_add_f32 v[66:67], v[70:71], v[68:69]
	v_mul_f32_e32 v68, v20, v20
	v_mul_f32_e32 v69, v21, v21
	v_pk_add_f32 v[66:67], v[66:67], v[66:67] op_sel:[0,1] op_sel_hi:[1,0]
	v_mov_b32_e32 v65, v68
	v_mov_b32_e32 v67, v69
	v_pk_add_f32 v[64:65], v[64:65], v[66:67]
	v_mul_f32_e32 v66, v25, v25
	v_mul_f32_e32 v68, v27, v27
	v_mul_f32_e32 v70, v22, v22
	v_mul_f32_e32 v71, v23, v23
	v_pk_fma_f32 v[66:67], v[24:25], v[24:25], v[66:67] op_sel_hi:[1,1,0]
	v_pk_fma_f32 v[68:69], v[26:27], v[26:27], v[68:69] op_sel_hi:[1,1,0]
	v_mov_b32_e32 v67, v70
	v_mov_b32_e32 v69, v71
	v_pk_add_f32 v[66:67], v[66:67], v[68:69]
	v_pk_mul_f32 v[68:69], v[16:17], v[16:17]
	v_pk_add_f32 v[64:65], v[64:65], v[66:67]
	v_pk_mul_f32 v[66:67], v[18:19], v[18:19]
	v_pk_add_f32 v[64:65], v[64:65], v[64:65] op_sel:[0,1] op_sel_hi:[1,0]
	v_pk_mov_b32 v[70:71], v[68:69], v[66:67] op_sel:[1,0]
	v_mov_b32_e32 v69, v67
	v_pk_add_f32 v[66:67], v[70:71], v[68:69]
	v_mul_f32_e32 v68, v40, v40
	v_mul_f32_e32 v69, v41, v41
	v_pk_add_f32 v[66:67], v[66:67], v[66:67] op_sel:[0,1] op_sel_hi:[1,0]
	v_mov_b32_e32 v65, v68
	v_mov_b32_e32 v67, v69
	v_pk_add_f32 v[64:65], v[64:65], v[66:67]
	v_mul_f32_e32 v66, v45, v45
	v_mul_f32_e32 v68, v47, v47
	v_mul_f32_e32 v70, v42, v42
	v_mul_f32_e32 v71, v43, v43
	v_pk_fma_f32 v[66:67], v[44:45], v[44:45], v[66:67] op_sel_hi:[1,1,0]
	v_pk_fma_f32 v[68:69], v[46:47], v[46:47], v[68:69] op_sel_hi:[1,1,0]
	v_mov_b32_e32 v67, v70
	v_mov_b32_e32 v69, v71
	v_pk_add_f32 v[66:67], v[66:67], v[68:69]
	v_pk_mul_f32 v[68:69], v[36:37], v[36:37]
	v_pk_add_f32 v[64:65], v[64:65], v[66:67]
	v_pk_mul_f32 v[66:67], v[38:39], v[38:39]
	v_pk_add_f32 v[64:65], v[64:65], v[64:65] op_sel:[0,1] op_sel_hi:[1,0]
	v_pk_mov_b32 v[70:71], v[68:69], v[66:67] op_sel:[1,0]
	v_mov_b32_e32 v69, v67
	v_pk_add_f32 v[66:67], v[70:71], v[68:69]
	v_mul_f32_e32 v68, v60, v60
	v_mul_f32_e32 v69, v61, v61
	v_pk_add_f32 v[66:67], v[66:67], v[66:67] op_sel:[0,1] op_sel_hi:[1,0]
	v_mov_b32_e32 v65, v68
	v_mov_b32_e32 v67, v69
	v_pk_add_f32 v[64:65], v[64:65], v[66:67]
	v_mul_f32_e32 v66, v33, v33
	v_mul_f32_e32 v68, v35, v35
	v_mul_f32_e32 v70, v62, v62
	v_mul_f32_e32 v71, v63, v63
	v_pk_fma_f32 v[66:67], v[32:33], v[32:33], v[66:67] op_sel_hi:[1,1,0]
	v_pk_fma_f32 v[68:69], v[34:35], v[34:35], v[68:69] op_sel_hi:[1,1,0]
	v_mov_b32_e32 v67, v70
	v_mov_b32_e32 v69, v71
	v_pk_add_f32 v[66:67], v[66:67], v[68:69]
	v_pk_mul_f32 v[68:69], v[56:57], v[56:57]
	v_pk_add_f32 v[64:65], v[64:65], v[66:67]
	v_pk_mul_f32 v[66:67], v[58:59], v[58:59]
	v_pk_add_f32 v[64:65], v[64:65], v[64:65] op_sel:[0,1] op_sel_hi:[1,0]
	v_pk_mov_b32 v[70:71], v[68:69], v[66:67] op_sel:[1,0]
	v_mov_b32_e32 v69, v67
	v_pk_add_f32 v[66:67], v[70:71], v[68:69]
	v_mul_f32_e32 v68, v48, v48
	v_mul_f32_e32 v69, v49, v49
	v_pk_add_f32 v[66:67], v[66:67], v[66:67] op_sel:[0,1] op_sel_hi:[1,0]
	v_mov_b32_e32 v65, v68
	v_mov_b32_e32 v67, v69
	v_pk_add_f32 v[64:65], v[64:65], v[66:67]
	v_mul_f32_e32 v66, v53, v53
	v_mul_f32_e32 v68, v55, v55
	v_mul_f32_e32 v70, v50, v50
	v_mul_f32_e32 v71, v51, v51
	v_pk_fma_f32 v[66:67], v[52:53], v[52:53], v[66:67] op_sel_hi:[1,1,0]
	v_pk_fma_f32 v[68:69], v[54:55], v[54:55], v[68:69] op_sel_hi:[1,1,0]
	v_mov_b32_e32 v67, v70
	v_mov_b32_e32 v69, v71
	v_pk_add_f32 v[66:67], v[66:67], v[68:69]
	v_and_b32_e32 v68, 64, v245
	v_pk_add_f32 v[64:65], v[64:65], v[66:67]
	v_xor_b32_e32 v67, 16, v245
	v_add_u32_e32 v68, 64, v68
	v_cmp_lt_i32_e32 vcc, v67, v68
	v_add_f32_e32 v66, v64, v65
	v_lshl_add_u64 v[64:65], s[84:85], 0, v[134:135]
	v_cndmask_b32_e32 v67, v245, v67, vcc
	v_lshlrev_b32_e32 v67, 2, v67
	ds_bpermute_b32 v67, v67, v66
	v_lshl_add_u64 v[64:65], v[64:65], 0, v[132:133]
	s_waitcnt lgkmcnt(0)
	v_add_f32_e32 v66, v66, v67
	v_xor_b32_e32 v67, 32, v245
	v_cmp_lt_i32_e32 vcc, v67, v68
	v_lshl_add_u64 v[68:69], v[64:65], 0, s[18:19]
	s_nop 0
	v_cndmask_b32_e32 v67, v245, v67, vcc
	v_lshlrev_b32_e32 v67, 2, v67
	ds_bpermute_b32 v67, v67, v66
	s_waitcnt lgkmcnt(0)
	v_add_f32_e32 v66, v66, v67
	v_fmamk_f32 v66, v66, 0x3b800000, v244
	v_cmp_gt_f32_e32 vcc, s7, v66
	v_mul_f32_e32 v67, 0x4b800000, v66
	s_nop 0
	v_cndmask_b32_e32 v66, v66, v67, vcc
	v_rsq_f32_e32 v66, v66
	s_nop 0
	v_mul_f32_e32 v67, 0x45800000, v66
	v_cndmask_b32_e32 v66, v66, v67, vcc
	v_mbcnt_lo_u32_b32 v78, -1, 0
	v_mbcnt_hi_u32_b32 v78, -1, v78
	v_lshrrev_b32_e32 v78, 4, v78
	v_and_b32_e32 v78, 1, v78
	v_mul_u32_u24_e32 v78, 24, v78
	v_mov_b32_e32 v79, v209
	v_lshl_add_u64 v[80:81], v[68:69], 0, v[78:79]
	v_mul_f32_e32 v12, v12, v66
	v_mul_f32_e32 v13, v13, v66
	v_cvt_pk_bf16_f32 v122, v12, v13
	v_mul_f32_e32 v14, v14, v66
	v_mul_f32_e32 v15, v15, v66
	v_cvt_pk_bf16_f32 v123, v14, v15
	v_mul_f32_e32 v8, v8, v66
	v_mul_f32_e32 v9, v9, v66
	v_cvt_pk_bf16_f32 v124, v8, v9
	v_mul_f32_e32 v10, v10, v66
	v_mul_f32_e32 v11, v11, v66
	v_cvt_pk_bf16_f32 v125, v10, v11
	s_nop 1
	v_permlane16_swap_b32_e32 v122, v124
	v_permlane16_swap_b32_e32 v123, v125
	global_store_dwordx4 v[80:81], v[122:125], off
	v_mul_f32_e32 v4, v4, v66
	v_mul_f32_e32 v5, v5, v66
	v_cvt_pk_bf16_f32 v126, v4, v5
	v_mul_f32_e32 v6, v6, v66
	v_mul_f32_e32 v7, v7, v66
	v_cvt_pk_bf16_f32 v127, v6, v7
	v_mul_f32_e32 v0, v0, v66
	v_mul_f32_e32 v1, v1, v66
	v_cvt_pk_bf16_f32 v128, v0, v1
	v_mul_f32_e32 v2, v2, v66
	v_mul_f32_e32 v3, v3, v66
	v_cvt_pk_bf16_f32 v129, v2, v3
	s_nop 1
	v_permlane16_swap_b32_e32 v126, v128
	v_permlane16_swap_b32_e32 v127, v129
	global_store_dwordx4 v[80:81], v[126:129], off offset:64
	v_mul_f32_e32 v28, v28, v66
	v_mul_f32_e32 v29, v29, v66
	v_cvt_pk_bf16_f32 v122, v28, v29
	v_mul_f32_e32 v30, v30, v66
	v_mul_f32_e32 v31, v31, v66
	v_cvt_pk_bf16_f32 v123, v30, v31
	v_mul_f32_e32 v24, v24, v66
	v_mul_f32_e32 v25, v25, v66
	v_cvt_pk_bf16_f32 v124, v24, v25
	v_mul_f32_e32 v26, v26, v66
	v_mul_f32_e32 v27, v27, v66
	v_cvt_pk_bf16_f32 v125, v26, v27
	s_nop 1
	v_permlane16_swap_b32_e32 v122, v124
	v_permlane16_swap_b32_e32 v123, v125
	global_store_dwordx4 v[80:81], v[122:125], off offset:128
	v_mul_f32_e32 v20, v20, v66
	v_mul_f32_e32 v21, v21, v66
	v_cvt_pk_bf16_f32 v126, v20, v21
	v_mul_f32_e32 v22, v22, v66
	v_mul_f32_e32 v23, v23, v66
	v_cvt_pk_bf16_f32 v127, v22, v23
	v_mul_f32_e32 v16, v16, v66
	v_mul_f32_e32 v17, v17, v66
	v_cvt_pk_bf16_f32 v128, v16, v17
	v_mul_f32_e32 v18, v18, v66
	v_mul_f32_e32 v19, v19, v66
	v_cvt_pk_bf16_f32 v129, v18, v19
	s_nop 1
	v_permlane16_swap_b32_e32 v126, v128
	v_permlane16_swap_b32_e32 v127, v129
	global_store_dwordx4 v[80:81], v[126:129], off offset:192
	v_mul_f32_e32 v44, v44, v66
	v_mul_f32_e32 v45, v45, v66
	v_cvt_pk_bf16_f32 v122, v44, v45
	v_mul_f32_e32 v46, v46, v66
	v_mul_f32_e32 v47, v47, v66
	v_cvt_pk_bf16_f32 v123, v46, v47
	v_mul_f32_e32 v40, v40, v66
	v_mul_f32_e32 v41, v41, v66
	v_cvt_pk_bf16_f32 v124, v40, v41
	v_mul_f32_e32 v42, v42, v66
	v_mul_f32_e32 v43, v43, v66
	v_cvt_pk_bf16_f32 v125, v42, v43
	s_nop 1
	v_permlane16_swap_b32_e32 v122, v124
	v_permlane16_swap_b32_e32 v123, v125
	global_store_dwordx4 v[80:81], v[122:125], off offset:256
	v_mul_f32_e32 v36, v36, v66
	v_mul_f32_e32 v37, v37, v66
	v_cvt_pk_bf16_f32 v126, v36, v37
	v_mul_f32_e32 v38, v38, v66
	v_mul_f32_e32 v39, v39, v66
	v_cvt_pk_bf16_f32 v127, v38, v39
	v_mul_f32_e32 v32, v32, v66
	v_mul_f32_e32 v33, v33, v66
	v_cvt_pk_bf16_f32 v128, v32, v33
	v_mul_f32_e32 v34, v34, v66
	v_mul_f32_e32 v35, v35, v66
	v_cvt_pk_bf16_f32 v129, v34, v35
	s_nop 1
	v_permlane16_swap_b32_e32 v126, v128
	v_permlane16_swap_b32_e32 v127, v129
	global_store_dwordx4 v[80:81], v[126:129], off offset:320
	v_mul_f32_e32 v60, v60, v66
	v_mul_f32_e32 v61, v61, v66
	v_cvt_pk_bf16_f32 v122, v60, v61
	v_mul_f32_e32 v62, v62, v66
	v_mul_f32_e32 v63, v63, v66
	v_cvt_pk_bf16_f32 v123, v62, v63
	v_mul_f32_e32 v56, v56, v66
	v_mul_f32_e32 v57, v57, v66
	v_cvt_pk_bf16_f32 v124, v56, v57
	v_mul_f32_e32 v58, v58, v66
	v_mul_f32_e32 v59, v59, v66
	v_cvt_pk_bf16_f32 v125, v58, v59
	s_nop 1
	v_permlane16_swap_b32_e32 v122, v124
	v_permlane16_swap_b32_e32 v123, v125
	global_store_dwordx4 v[80:81], v[122:125], off offset:384
	v_mul_f32_e32 v52, v52, v66
	v_mul_f32_e32 v53, v53, v66
	v_cvt_pk_bf16_f32 v126, v52, v53
	v_mul_f32_e32 v54, v54, v66
	v_mul_f32_e32 v55, v55, v66
	v_cvt_pk_bf16_f32 v127, v54, v55
	v_mul_f32_e32 v48, v48, v66
	v_mul_f32_e32 v49, v49, v66
	v_cvt_pk_bf16_f32 v128, v48, v49
	v_mul_f32_e32 v50, v50, v66
	v_mul_f32_e32 v51, v51, v66
	v_cvt_pk_bf16_f32 v129, v50, v51
	s_nop 1
	v_permlane16_swap_b32_e32 v126, v128
	v_permlane16_swap_b32_e32 v127, v129
	global_store_dwordx4 v[80:81], v[126:129], off offset:448
	s_waitcnt lgkmcnt(0)
	s_cbranch_scc1 .LBB0_235
	v_readlane_b32 s16, v253, 49
	s_mov_b64 s[36:37], 0xc000800

.LBB0_362:
	global_load_dwordx4 v[104:107], v[80:81], off
	global_load_dwordx4 v[116:119], v[80:81], off offset:2048
	global_load_dwordx4 v[120:123], v[82:83], off
	global_load_dwordx4 v[132:135], v[84:85], off
	s_ashr_i32 s11, s3, 31
	s_lshr_b32 s11, s11, 19
	s_add_i32 s11, s3, s11
	s_and_b32 s11, s11, 0xffffe000
	s_sub_i32 s11, s3, s11
	v_or_b32_e32 v0, s11, v158
	s_ashr_i32 s11, s0, 31
	s_lshr_b32 s11, s11, 23
	s_add_i32 s11, s0, s11
	s_ashr_i32 s11, s11, 9
	s_mul_i32 s18, s11, 0x84
	s_ashr_i32 s19, s18, 31
	v_sub_u32_e32 v1, 0, v0
	s_lshl_b64 s[18:19], s[18:19], 15
	v_and_b32_e32 v2, 0x1fff, v1
	v_ashrrev_i32_e32 v1, 31, v0
	s_add_u32 s22, s16, s18
	s_addc_u32 s23, s33, s19
	v_lshlrev_b64 v[56:57], 2, v[0:1]
	v_lshlrev_b32_e32 v208, 2, v2
	s_mov_b32 s100, 0x0
	v_add3_u32 v252, v56, v64, s100
	global_load_dword v136, v252, s[22:23]
	v_add3_u32 v252, v56, v66, s100
	global_load_dword v137, v252, s[22:23]
	v_add3_u32 v252, v56, v68, s100
	global_load_dword v138, v252, s[22:23]
	v_add3_u32 v252, v56, v70, s100
	global_load_dword v139, v252, s[22:23]
	v_add3_u32 v252, v56, v72, s100
	global_load_dword v148, v252, s[22:23]
	v_add3_u32 v252, v56, v74, s100
	global_load_dword v149, v252, s[22:23]
	v_add3_u32 v252, v56, v76, s100
	global_load_dword v150, v252, s[22:23]
	v_add3_u32 v252, v56, v78, s100
	global_load_dword v151, v252, s[22:23]
	s_mov_b32 s100, 0x0
	v_add3_u32 v252, v56, v88, s100
	v_add3_u32 v169, v208, v86, s100
	v_cndmask_b32_e32 v252, v169, v252, vcc
	global_load_dword v152, v252, s[22:23]
	v_add3_u32 v252, v208, v90, s100
	global_load_dword v153, v252, s[22:23]
	v_add3_u32 v252, v208, v92, s100
	global_load_dword v154, v252, s[22:23]
	v_add3_u32 v252, v208, v94, s100
	global_load_dword v155, v252, s[22:23]
	v_add3_u32 v252, v208, v96, s100
	global_load_dword v250, v252, s[22:23]
	v_add3_u32 v252, v208, v98, s100
	global_load_dword v251, v252, s[22:23]
	v_add3_u32 v252, v208, v100, s100
	global_load_dword v170, v252, s[22:23]
	v_add3_u32 v252, v208, v102, s100
	global_load_dword v171, v252, s[22:23]
	s_mov_b32 s100, 0x108000
	v_add3_u32 v252, v56, v64, s100
	global_load_dword v172, v252, s[22:23]
	v_add3_u32 v252, v56, v66, s100
	global_load_dword v173, v252, s[22:23]
	v_add3_u32 v252, v56, v68, s100
	global_load_dword v174, v252, s[22:23]
	v_add3_u32 v252, v56, v70, s100
	global_load_dword v175, v252, s[22:23]
	v_add3_u32 v252, v56, v72, s100
	global_load_dword v65, v252, s[22:23]
	v_add3_u32 v252, v56, v74, s100
	global_load_dword v67, v252, s[22:23]
	v_add3_u32 v252, v56, v76, s100
	global_load_dword v69, v252, s[22:23]
	v_add3_u32 v252, v56, v78, s100
	global_load_dword v71, v252, s[22:23]
	s_mov_b64 s[18:19], 0x1a000400
	s_add_i32 s0, s0, s2
	s_waitcnt vmcnt(16)
	v_cvt_pk_bf16_f32 v0, v136, v137
	v_cvt_pk_bf16_f32 v1, v138, v139
	v_cvt_pk_bf16_f32 v2, v148, v149
	v_cvt_pk_bf16_f32 v3, v150, v151
	s_mov_b32 s100, 0x108000
	v_add3_u32 v252, v56, v88, s100
	v_add3_u32 v169, v208, v86, s100
	v_cndmask_b32_e32 v252, v169, v252, vcc
	global_load_dword v136, v252, s[22:23]
	v_add3_u32 v252, v208, v90, s100
	global_load_dword v137, v252, s[22:23]
	v_add3_u32 v252, v208, v92, s100
	global_load_dword v138, v252, s[22:23]
	v_add3_u32 v252, v208, v94, s100
	global_load_dword v139, v252, s[22:23]
	v_add3_u32 v252, v208, v96, s100
	global_load_dword v148, v252, s[22:23]
	v_add3_u32 v252, v208, v98, s100
	global_load_dword v149, v252, s[22:23]
	v_add3_u32 v252, v208, v100, s100
	global_load_dword v150, v252, s[22:23]
	v_add3_u32 v252, v208, v102, s100
	global_load_dword v151, v252, s[22:23]
	v_mfma_f32_16x16x32_bf16 v[4:7], v[104:107], v[0:3], 0
	v_mfma_f32_16x16x32_bf16 v[8:11], v[116:119], v[0:3], 0
	v_mfma_f32_16x16x32_bf16 v[12:15], v[120:123], v[0:3], 0
	v_mfma_f32_16x16x32_bf16 v[0:3], v[132:135], v[0:3], 0
	global_load_dwordx4 v[104:107], v[112:113], off
	global_load_dwordx4 v[116:119], v[108:109], off
	global_load_dwordx4 v[120:123], v[110:111], off
	global_load_dwordx4 v[132:135], v[114:115], off
	s_waitcnt vmcnt(20)
	v_cvt_pk_bf16_f32 v16, v152, v153
	v_cvt_pk_bf16_f32 v17, v154, v155
	v_cvt_pk_bf16_f32 v18, v250, v251
	v_cvt_pk_bf16_f32 v19, v170, v171
	s_mov_b32 s100, 0x210000
	v_add3_u32 v252, v56, v64, s100
	global_load_dword v152, v252, s[22:23]
	v_add3_u32 v252, v56, v66, s100
	global_load_dword v153, v252, s[22:23]
	v_add3_u32 v252, v56, v68, s100
	global_load_dword v154, v252, s[22:23]
	v_add3_u32 v252, v56, v70, s100
	global_load_dword v155, v252, s[22:23]
	v_add3_u32 v252, v56, v72, s100
	global_load_dword v250, v252, s[22:23]
	v_add3_u32 v252, v56, v74, s100
	global_load_dword v251, v252, s[22:23]
	v_add3_u32 v252, v56, v76, s100
	global_load_dword v170, v252, s[22:23]
	v_add3_u32 v252, v56, v78, s100
	global_load_dword v171, v252, s[22:23]
	v_mfma_f32_16x16x32_bf16 v[24:27], v[176:179], v[16:19], v[4:7]
	s_nop 2
	v_mfma_f32_16x16x32_bf16 v[8:11], v[180:183], v[16:19], v[8:11]
	v_mfma_f32_16x16x32_bf16 v[4:7], v[184:187], v[16:19], v[12:15]
	s_nop 2
	v_mfma_f32_16x16x32_bf16 v[0:3], v[188:191], v[16:19], v[0:3]
	s_waitcnt vmcnt(8)
	v_cvt_pk_bf16_f32 v12, v172, v173
	v_cvt_pk_bf16_f32 v13, v174, v175
	v_cvt_pk_bf16_f32 v14, v65, v67
	v_cvt_pk_bf16_f32 v15, v69, v71
	s_mov_b32 s100, 0x210000
	v_add3_u32 v252, v56, v88, s100
	v_add3_u32 v169, v208, v86, s100
	v_cndmask_b32_e32 v252, v169, v252, vcc
	global_load_dword v172, v252, s[22:23]
	v_add3_u32 v252, v208, v90, s100
	global_load_dword v173, v252, s[22:23]
	v_add3_u32 v252, v208, v92, s100
	global_load_dword v174, v252, s[22:23]
	v_add3_u32 v252, v208, v94, s100
	global_load_dword v175, v252, s[22:23]
	v_add3_u32 v252, v208, v96, s100
	global_load_dword v65, v252, s[22:23]
	v_add3_u32 v252, v208, v98, s100
	global_load_dword v67, v252, s[22:23]
	v_add3_u32 v252, v208, v100, s100
	global_load_dword v69, v252, s[22:23]
	v_add3_u32 v252, v208, v102, s100
	global_load_dword v71, v252, s[22:23]
	v_mfma_f32_16x16x32_bf16 v[32:35], v[104:107], v[12:15], 0
	v_mfma_f32_16x16x32_bf16 v[16:19], v[116:119], v[12:15], 0
	v_mfma_f32_16x16x32_bf16 v[20:23], v[120:123], v[12:15], 0
	v_mfma_f32_16x16x32_bf16 v[12:15], v[132:135], v[12:15], 0
	global_load_dwordx4 v[104:107], v[128:129], off
	global_load_dwordx4 v[116:119], v[124:125], off
	global_load_dwordx4 v[120:123], v[126:127], off
	global_load_dwordx4 v[132:135], v[130:131], off
	s_waitcnt vmcnt(24)
	v_cvt_pk_bf16_f32 v36, v136, v137
	v_cvt_pk_bf16_f32 v37, v138, v139
	v_cvt_pk_bf16_f32 v38, v148, v149
	v_cvt_pk_bf16_f32 v39, v150, v151
	s_mov_b32 s100, 0x318000
	v_add3_u32 v252, v56, v64, s100
	global_load_dword v136, v252, s[22:23]
	v_add3_u32 v252, v56, v66, s100
	global_load_dword v137, v252, s[22:23]
	v_add3_u32 v252, v56, v68, s100
	global_load_dword v138, v252, s[22:23]
	v_add3_u32 v252, v56, v70, s100
	global_load_dword v139, v252, s[22:23]
	v_add3_u32 v252, v56, v72, s100
	global_load_dword v148, v252, s[22:23]
	v_add3_u32 v252, v56, v74, s100
	global_load_dword v149, v252, s[22:23]
	v_add3_u32 v252, v56, v76, s100
	global_load_dword v150, v252, s[22:23]
	v_add3_u32 v252, v56, v78, s100
	global_load_dword v151, v252, s[22:23]
	v_mfma_f32_16x16x32_bf16 v[28:31], v[192:195], v[36:39], v[16:19]
	s_nop 2
	v_mfma_f32_16x16x32_bf16 v[20:23], v[196:199], v[36:39], v[20:23]
	v_mfma_f32_16x16x32_bf16 v[16:19], v[200:203], v[36:39], v[32:35]
	s_nop 2
	v_mfma_f32_16x16x32_bf16 v[12:15], v[204:207], v[36:39], v[12:15]
	s_waitcnt vmcnt(8)
	v_cvt_pk_bf16_f32 v32, v152, v153
	v_cvt_pk_bf16_f32 v33, v154, v155
	v_cvt_pk_bf16_f32 v34, v250, v251
	v_cvt_pk_bf16_f32 v35, v170, v171
	s_mov_b32 s100, 0x318000
	v_add3_u32 v252, v56, v88, s100
	v_add3_u32 v169, v208, v86, s100
	v_cndmask_b32_e32 v252, v169, v252, vcc
	global_load_dword v152, v252, s[22:23]
	v_add3_u32 v252, v208, v90, s100
	global_load_dword v153, v252, s[22:23]
	v_add3_u32 v252, v208, v92, s100
	global_load_dword v154, v252, s[22:23]
	v_add3_u32 v252, v208, v94, s100
	global_load_dword v155, v252, s[22:23]
	v_add3_u32 v252, v208, v96, s100
	global_load_dword v250, v252, s[22:23]
	v_add3_u32 v252, v208, v98, s100
	global_load_dword v251, v252, s[22:23]
	v_add3_u32 v252, v208, v100, s100
	global_load_dword v170, v252, s[22:23]
	v_add3_u32 v252, v208, v102, s100
	global_load_dword v171, v252, s[22:23]
	v_mfma_f32_16x16x32_bf16 v[48:51], v[104:107], v[32:35], 0
	v_mfma_f32_16x16x32_bf16 v[36:39], v[116:119], v[32:35], 0
	v_mfma_f32_16x16x32_bf16 v[40:43], v[120:123], v[32:35], 0
	v_mfma_f32_16x16x32_bf16 v[32:35], v[132:135], v[32:35], 0
	global_load_dwordx4 v[104:107], v[144:145], off
	global_load_dwordx4 v[116:119], v[140:141], off
	global_load_dwordx4 v[120:123], v[142:143], off
	global_load_dwordx4 v[132:135], v[146:147], off
	s_waitcnt vmcnt(24)
	v_cvt_pk_bf16_f32 v52, v172, v173
	v_cvt_pk_bf16_f32 v53, v174, v175
	v_cvt_pk_bf16_f32 v54, v65, v67
	v_cvt_pk_bf16_f32 v55, v69, v71
	s_nop 1
	v_mfma_f32_16x16x32_bf16 v[44:47], v[214:217], v[52:55], v[36:39]
	s_nop 2
	v_mfma_f32_16x16x32_bf16 v[40:43], v[218:221], v[52:55], v[40:43]
	v_mfma_f32_16x16x32_bf16 v[36:39], v[222:225], v[52:55], v[48:51]
	s_nop 2
	v_mfma_f32_16x16x32_bf16 v[32:35], v[226:229], v[52:55], v[32:35]
	s_waitcnt vmcnt(0)
	v_cvt_pk_bf16_f32 v48, v136, v137
	v_cvt_pk_bf16_f32 v49, v138, v139
	v_cvt_pk_bf16_f32 v50, v148, v149
	v_cvt_pk_bf16_f32 v51, v150, v151
	s_nop 1
	v_mfma_f32_16x16x32_bf16 v[160:163], v[104:107], v[48:51], 0
	v_mfma_f32_16x16x32_bf16 v[52:55], v[116:119], v[48:51], 0
	v_mfma_f32_16x16x32_bf16 v[56:59], v[120:123], v[48:51], 0
	v_mfma_f32_16x16x32_bf16 v[48:51], v[132:135], v[48:51], 0
	s_waitcnt vmcnt(4)
	v_cvt_pk_bf16_f32 v164, v152, v153
	v_cvt_pk_bf16_f32 v165, v154, v155
	v_cvt_pk_bf16_f32 v166, v250, v251
	v_cvt_pk_bf16_f32 v167, v170, v171
	s_nop 1
	v_mul_f32_e32 v157, v0, v0
	v_mul_f32_e32 v159, v1, v1
	v_mfma_f32_16x16x32_bf16 v[60:63], v[230:233], v[164:167], v[52:55]
	s_nop 2
	v_mfma_f32_16x16x32_bf16 v[56:59], v[234:237], v[164:167], v[56:59]
	v_mfma_f32_16x16x32_bf16 v[52:55], v[238:241], v[164:167], v[160:163]
	s_nop 2
	v_mfma_f32_16x16x32_bf16 v[48:51], v[246:249], v[164:167], v[48:51]
	v_mul_f32_e64 v160, v26, v26
	v_mul_f32_e64 v161, v27, v27
	v_pk_mul_f32 v[162:163], v[24:25], v[24:25]
	s_nop 0
	v_pk_mov_b32 v[164:165], v[162:163], v[160:161] op_sel:[1,0]
	v_mov_b32_e32 v163, v161
	v_pk_add_f32 v[160:161], v[164:165], v[162:163]
	v_pk_mul_f32 v[162:163], v[10:11], v[10:11]
	v_pk_mul_f32 v[164:165], v[8:9], v[8:9]
	v_pk_add_f32 v[160:161], v[160:161], v[160:161] op_sel:[0,1] op_sel_hi:[1,0]
	v_pk_mov_b32 v[166:167], v[164:165], v[162:163] op_sel:[1,0]
	v_mov_b32_e32 v165, v163
	v_pk_add_f32 v[162:163], v[166:167], v[164:165]
	v_mov_b32_e32 v161, v157
	v_pk_add_f32 v[162:163], v[162:163], v[162:163] op_sel:[0,1] op_sel_hi:[1,0]
	v_mul_f32_e32 v164, v2, v2
	v_mov_b32_e32 v163, v159
	v_pk_add_f32 v[160:161], v[160:161], v[162:163]
	v_mul_f32_e32 v162, v5, v5
	v_pk_fma_f32 v[162:163], v[4:5], v[4:5], v[162:163] op_sel_hi:[1,1,0]
	v_mul_f32_e32 v166, v3, v3
	v_mov_b32_e32 v163, v164
	v_mul_f32_e32 v164, v7, v7
	v_pk_fma_f32 v[164:165], v[6:7], v[6:7], v[164:165] op_sel_hi:[1,1,0]
	v_mul_f32_e32 v157, v16, v16
	v_mov_b32_e32 v165, v166
	v_pk_add_f32 v[162:163], v[162:163], v[164:165]
	v_pk_mul_f32 v[164:165], v[28:29], v[28:29]
	v_pk_add_f32 v[160:161], v[160:161], v[162:163]
	v_pk_mul_f32 v[162:163], v[30:31], v[30:31]
	v_mul_f32_e32 v159, v17, v17
	v_pk_mov_b32 v[166:167], v[164:165], v[162:163] op_sel:[1,0]
	v_mov_b32_e32 v165, v163
	v_pk_add_f32 v[162:163], v[166:167], v[164:165]
	v_pk_add_f32 v[160:161], v[160:161], v[160:161] op_sel:[0,1] op_sel_hi:[1,0]
	v_pk_add_f32 v[162:163], v[162:163], v[162:163] op_sel:[0,1] op_sel_hi:[1,0]
	v_mov_b32_e32 v161, v157
	v_mov_b32_e32 v163, v159
	v_pk_add_f32 v[160:161], v[160:161], v[162:163]
	v_mul_f32_e32 v162, v21, v21
	v_mul_f32_e32 v164, v18, v18
	v_pk_fma_f32 v[162:163], v[20:21], v[20:21], v[162:163] op_sel_hi:[1,1,0]
	v_mul_f32_e32 v166, v19, v19
	v_mov_b32_e32 v163, v164
	v_mul_f32_e32 v164, v23, v23
	v_pk_fma_f32 v[164:165], v[22:23], v[22:23], v[164:165] op_sel_hi:[1,1,0]
	v_mul_f32_e32 v157, v40, v40
	v_mov_b32_e32 v165, v166
	v_pk_add_f32 v[162:163], v[162:163], v[164:165]
	v_pk_mul_f32 v[164:165], v[12:13], v[12:13]
	v_pk_add_f32 v[160:161], v[160:161], v[162:163]
	v_pk_mul_f32 v[162:163], v[14:15], v[14:15]
	v_mul_f32_e32 v159, v41, v41
	v_pk_mov_b32 v[166:167], v[164:165], v[162:163] op_sel:[1,0]
	v_mov_b32_e32 v165, v163
	v_pk_add_f32 v[162:163], v[166:167], v[164:165]
	v_pk_add_f32 v[160:161], v[160:161], v[160:161] op_sel:[0,1] op_sel_hi:[1,0]
	v_pk_add_f32 v[162:163], v[162:163], v[162:163] op_sel:[0,1] op_sel_hi:[1,0]
	v_mov_b32_e32 v161, v157
	v_mov_b32_e32 v163, v159
	v_pk_add_f32 v[160:161], v[160:161], v[162:163]
	v_mul_f32_e32 v162, v45, v45
	v_mul_f32_e32 v164, v42, v42
	v_pk_fma_f32 v[162:163], v[44:45], v[44:45], v[162:163] op_sel_hi:[1,1,0]
	v_mul_f32_e32 v166, v43, v43
	v_mov_b32_e32 v163, v164
	v_mul_f32_e32 v164, v47, v47
	v_pk_fma_f32 v[164:165], v[46:47], v[46:47], v[164:165] op_sel_hi:[1,1,0]
	v_mul_f32_e32 v157, v60, v60
	v_mov_b32_e32 v165, v166
	v_pk_add_f32 v[162:163], v[162:163], v[164:165]
	v_pk_mul_f32 v[164:165], v[36:37], v[36:37]
	v_pk_add_f32 v[160:161], v[160:161], v[162:163]
	v_pk_mul_f32 v[162:163], v[38:39], v[38:39]
	v_mul_f32_e32 v159, v61, v61
	v_pk_mov_b32 v[166:167], v[164:165], v[162:163] op_sel:[1,0]
	v_mov_b32_e32 v165, v163
	v_pk_add_f32 v[162:163], v[166:167], v[164:165]
	v_pk_add_f32 v[160:161], v[160:161], v[160:161] op_sel:[0,1] op_sel_hi:[1,0]
	v_pk_add_f32 v[162:163], v[162:163], v[162:163] op_sel:[0,1] op_sel_hi:[1,0]
	v_mov_b32_e32 v161, v157
	v_mov_b32_e32 v163, v159
	v_pk_add_f32 v[160:161], v[160:161], v[162:163]
	v_mul_f32_e32 v162, v33, v33
	v_mul_f32_e32 v164, v62, v62
	v_pk_fma_f32 v[162:163], v[32:33], v[32:33], v[162:163] op_sel_hi:[1,1,0]
	v_mul_f32_e32 v166, v63, v63
	v_mov_b32_e32 v163, v164
	v_mul_f32_e32 v164, v35, v35
	v_pk_fma_f32 v[164:165], v[34:35], v[34:35], v[164:165] op_sel_hi:[1,1,0]
	v_mul_f32_e32 v157, v48, v48
	v_mov_b32_e32 v165, v166
	v_pk_add_f32 v[162:163], v[162:163], v[164:165]
	v_pk_mul_f32 v[164:165], v[56:57], v[56:57]
	v_pk_add_f32 v[160:161], v[160:161], v[162:163]
	v_pk_mul_f32 v[162:163], v[58:59], v[58:59]
	v_mul_f32_e32 v159, v49, v49
	v_pk_mov_b32 v[166:167], v[164:165], v[162:163] op_sel:[1,0]
	v_mov_b32_e32 v165, v163
	v_pk_add_f32 v[162:163], v[166:167], v[164:165]
	v_pk_add_f32 v[160:161], v[160:161], v[160:161] op_sel:[0,1] op_sel_hi:[1,0]
	v_pk_add_f32 v[162:163], v[162:163], v[162:163] op_sel:[0,1] op_sel_hi:[1,0]
	v_mov_b32_e32 v161, v157
	v_mov_b32_e32 v163, v159
	v_pk_add_f32 v[160:161], v[160:161], v[162:163]
	v_mul_f32_e32 v162, v53, v53
	v_mul_f32_e32 v164, v50, v50
	v_pk_fma_f32 v[162:163], v[52:53], v[52:53], v[162:163] op_sel_hi:[1,1,0]
	v_mul_f32_e32 v166, v51, v51
	v_mov_b32_e32 v163, v164
	v_mul_f32_e32 v164, v55, v55
	v_pk_fma_f32 v[164:165], v[54:55], v[54:55], v[164:165] op_sel_hi:[1,1,0]
	v_xor_b32_e32 v159, 16, v245
	v_mov_b32_e32 v165, v166
	v_pk_add_f32 v[162:163], v[162:163], v[164:165]
	s_nop 0
	v_pk_add_f32 v[160:161], v[160:161], v[162:163]
	s_nop 0
	v_add_f32_e32 v157, v160, v161
	v_and_b32_e32 v160, 64, v245
	v_add_u32_e32 v160, 64, v160
	v_cmp_lt_i32_e64 s[36:37], v159, v160
	s_nop 1
	v_cndmask_b32_e64 v159, v245, v159, s[36:37]
	v_lshlrev_b32_e32 v159, 2, v159
	ds_bpermute_b32 v159, v159, v157
	s_waitcnt lgkmcnt(0)
	v_add_f32_e32 v157, v157, v159
	v_xor_b32_e32 v159, 32, v245
	v_cmp_lt_i32_e64 s[36:37], v159, v160
	v_add_u32_e32 v160, s3, v158
	v_ashrrev_i32_e32 v161, 31, v160
	v_cndmask_b32_e64 v159, v245, v159, s[36:37]
	v_lshlrev_b32_e32 v159, 2, v159
	ds_bpermute_b32 v159, v159, v157
	v_lshlrev_b64 v[160:161], 11, v[160:161]
	v_lshl_add_u64 v[160:161], s[84:85], 0, v[160:161]
	s_add_i32 s3, s3, s9
	s_cmpk_lt_i32 s0, 0x1000
	s_waitcnt lgkmcnt(0)
	v_add_f32_e32 v157, v157, v159
	v_fmamk_f32 v157, v157, 0x3b800000, v244
	v_cmp_gt_f32_e64 s[36:37], s7, v157
	v_mul_f32_e32 v159, 0x4b800000, v157
	s_nop 0
	v_cndmask_b32_e64 v157, v157, v159, s[36:37]
	v_rsq_f32_e32 v157, v157
	s_nop 0
	v_mul_f32_e32 v159, 0x45800000, v157
	v_cndmask_b32_e64 v159, v157, v159, s[36:37]
	v_mov_b32_e32 v157, v209
	v_lshl_add_u64 v[160:161], v[160:161], 0, v[156:157]
	v_lshl_add_u64 v[162:163], v[160:161], 0, s[18:19]
	v_mbcnt_lo_u32_b32 v154, -1, 0
	v_mbcnt_hi_u32_b32 v154, -1, v154
	v_lshrrev_b32_e32 v154, 4, v154
	v_and_b32_e32 v154, 1, v154
	v_mul_u32_u24_e32 v154, 24, v154
	v_mov_b32_e32 v155, v209
	v_lshl_add_u64 v[152:153], v[162:163], 0, v[154:155]
	v_mul_f32_e32 v24, v24, v159
	v_mul_f32_e32 v25, v25, v159
	v_cvt_pk_bf16_f32 v136, v24, v25
	v_mul_f32_e32 v26, v26, v159
	v_mul_f32_e32 v27, v27, v159
	v_cvt_pk_bf16_f32 v137, v26, v27
	v_mul_f32_e32 v8, v8, v159
	v_mul_f32_e32 v9, v9, v159
	v_cvt_pk_bf16_f32 v138, v8, v9
	v_mul_f32_e32 v10, v10, v159
	v_mul_f32_e32 v11, v11, v159
	v_cvt_pk_bf16_f32 v139, v10, v11
	s_nop 1
	v_permlane16_swap_b32_e32 v136, v138
	v_permlane16_swap_b32_e32 v137, v139
	global_store_dwordx4 v[152:153], v[136:139], off
	v_mul_f32_e32 v4, v4, v159
	v_mul_f32_e32 v5, v5, v159
	v_cvt_pk_bf16_f32 v148, v4, v5
	v_mul_f32_e32 v6, v6, v159
	v_mul_f32_e32 v7, v7, v159
	v_cvt_pk_bf16_f32 v149, v6, v7
	v_mul_f32_e32 v0, v0, v159
	v_mul_f32_e32 v1, v1, v159
	v_cvt_pk_bf16_f32 v150, v0, v1
	v_mul_f32_e32 v2, v2, v159
	v_mul_f32_e32 v3, v3, v159
	v_cvt_pk_bf16_f32 v151, v2, v3
	s_nop 1
	v_permlane16_swap_b32_e32 v148, v150
	v_permlane16_swap_b32_e32 v149, v151
	global_store_dwordx4 v[152:153], v[148:151], off offset:64
	v_mul_f32_e32 v28, v28, v159
	v_mul_f32_e32 v29, v29, v159
	v_cvt_pk_bf16_f32 v136, v28, v29
	v_mul_f32_e32 v30, v30, v159
	v_mul_f32_e32 v31, v31, v159
	v_cvt_pk_bf16_f32 v137, v30, v31
	v_mul_f32_e32 v20, v20, v159
	v_mul_f32_e32 v21, v21, v159
	v_cvt_pk_bf16_f32 v138, v20, v21
	v_mul_f32_e32 v22, v22, v159
	v_mul_f32_e32 v23, v23, v159
	v_cvt_pk_bf16_f32 v139, v22, v23
	s_nop 1
	v_permlane16_swap_b32_e32 v136, v138
	v_permlane16_swap_b32_e32 v137, v139
	global_store_dwordx4 v[152:153], v[136:139], off offset:128
	v_mul_f32_e32 v16, v16, v159
	v_mul_f32_e32 v17, v17, v159
	v_cvt_pk_bf16_f32 v148, v16, v17
	v_mul_f32_e32 v18, v18, v159
	v_mul_f32_e32 v19, v19, v159
	v_cvt_pk_bf16_f32 v149, v18, v19
	v_mul_f32_e32 v12, v12, v159
	v_mul_f32_e32 v13, v13, v159
	v_cvt_pk_bf16_f32 v150, v12, v13
	v_mul_f32_e32 v14, v14, v159
	v_mul_f32_e32 v15, v15, v159
	v_cvt_pk_bf16_f32 v151, v14, v15
	s_nop 1
	v_permlane16_swap_b32_e32 v148, v150
	v_permlane16_swap_b32_e32 v149, v151
	global_store_dwordx4 v[152:153], v[148:151], off offset:192
	v_mul_f32_e32 v44, v44, v159
	v_mul_f32_e32 v45, v45, v159
	v_cvt_pk_bf16_f32 v136, v44, v45
	v_mul_f32_e32 v46, v46, v159
	v_mul_f32_e32 v47, v47, v159
	v_cvt_pk_bf16_f32 v137, v46, v47
	v_mul_f32_e32 v40, v40, v159
	v_mul_f32_e32 v41, v41, v159
	v_cvt_pk_bf16_f32 v138, v40, v41
	v_mul_f32_e32 v42, v42, v159
	v_mul_f32_e32 v43, v43, v159
	v_cvt_pk_bf16_f32 v139, v42, v43
	s_nop 1
	v_permlane16_swap_b32_e32 v136, v138
	v_permlane16_swap_b32_e32 v137, v139
	global_store_dwordx4 v[152:153], v[136:139], off offset:256
	v_mul_f32_e32 v36, v36, v159
	v_mul_f32_e32 v37, v37, v159
	v_cvt_pk_bf16_f32 v148, v36, v37
	v_mul_f32_e32 v38, v38, v159
	v_mul_f32_e32 v39, v39, v159
	v_cvt_pk_bf16_f32 v149, v38, v39
	v_mul_f32_e32 v32, v32, v159
	v_mul_f32_e32 v33, v33, v159
	v_cvt_pk_bf16_f32 v150, v32, v33
	v_mul_f32_e32 v34, v34, v159
	v_mul_f32_e32 v35, v35, v159
	v_cvt_pk_bf16_f32 v151, v34, v35
	s_nop 1
	v_permlane16_swap_b32_e32 v148, v150
	v_permlane16_swap_b32_e32 v149, v151
	global_store_dwordx4 v[152:153], v[148:151], off offset:320
	v_mul_f32_e32 v60, v60, v159
	v_mul_f32_e32 v61, v61, v159
	v_cvt_pk_bf16_f32 v136, v60, v61
	v_mul_f32_e32 v62, v62, v159
	v_mul_f32_e32 v63, v63, v159
	v_cvt_pk_bf16_f32 v137, v62, v63
	v_mul_f32_e32 v56, v56, v159
	v_mul_f32_e32 v57, v57, v159
	v_cvt_pk_bf16_f32 v138, v56, v57
	v_mul_f32_e32 v58, v58, v159
	v_mul_f32_e32 v59, v59, v159
	v_cvt_pk_bf16_f32 v139, v58, v59
	s_nop 1
	v_permlane16_swap_b32_e32 v136, v138
	v_permlane16_swap_b32_e32 v137, v139
	global_store_dwordx4 v[152:153], v[136:139], off offset:384
	v_mul_f32_e32 v52, v52, v159
	v_mul_f32_e32 v53, v53, v159
	v_cvt_pk_bf16_f32 v148, v52, v53
	v_mul_f32_e32 v54, v54, v159
	v_mul_f32_e32 v55, v55, v159
	v_cvt_pk_bf16_f32 v149, v54, v55
	v_mul_f32_e32 v48, v48, v159
	v_mul_f32_e32 v49, v49, v159
	v_cvt_pk_bf16_f32 v150, v48, v49
	v_mul_f32_e32 v50, v50, v159
	v_mul_f32_e32 v51, v51, v159
	v_cvt_pk_bf16_f32 v151, v50, v51
	s_nop 1
	v_permlane16_swap_b32_e32 v148, v150
	v_permlane16_swap_b32_e32 v149, v151
	global_store_dwordx4 v[152:153], v[148:151], off offset:448
	s_cbranch_scc1 .LBB0_362
